# sgemm_sample in k3,k6,k10,k13 hand-rewritten: 4-stage global prefetch, units spread over CUs
# speedup vs baseline: 1.0292x; 1.0292x over previous
_Z10fwd_kernelILi3ELi4EEv4Args:
	v_mov_b32_e32 v1, v0
	s_load_dword s3, s[0:1], 0xe8
	s_load_dwordx2 s[0:1], s[0:1], 0xd8
	v_readfirstlane_b32 s4, v1
	s_ashr_i32 s4, s4, 6
	s_waitcnt lgkmcnt(0)
	s_add_u32 s6, s0, 0x700000
	s_addc_u32 s7, s1, 0
	s_mul_i32 s5, s4, s3
	s_add_i32 s12, s5, s2
	s_cmpk_gt_i32 s12, 0x1ff
	s_cbranch_scc1 .LBB3_3
	s_add_u32 s20, s0, 0xf700000
	s_addc_u32 s21, s1, 0
	s_add_u32 s22, s0, 0x7400000
	s_addc_u32 s23, s1, 0
	s_lshl_b32 s24, s3, 3
	v_and_b32_e32 v234, 31, v0
	v_bfe_u32 v235, v0, 5, 1
	v_lshlrev_b32_e32 v232, 11, v234
	v_lshl_add_u32 v232, v235, 4, v232
	v_lshlrev_b32_e32 v233, 2, v234
	v_lshl_add_u32 v233, v235, 14, v233
.Lsg3_unit:
	s_and_b32 s28, s12, 0xff
	s_lshr_b32 s29, s12, 8
	s_lshr_b32 s26, s28, 4
	s_bfe_u32 s25, s28, 0x10003
	s_and_b32 s27, s28, 7
	s_lshl_b32 s29, s29, 3
	s_add_u32 s27, s27, s29
	s_lshl_b32 s30, s25, 10
	s_lshl_b32 s31, s27, 16
	s_add_u32 s31, s31, s30
	s_lshl_b32 s33, s26, 17
	s_add_u32 s33, s33, s30
	v_add_u32_e32 v226, s31, v232
	v_add_u32_e32 v227, s33, v232
	v_add_u32_e32 v228, 0x10000, v227
	s_lshl_b32 s34, s25, 21
	s_lshl_b32 s35, s27, 17
	s_add_u32 s34, s34, s35
	s_lshl_b32 s35, s26, 8
	s_add_u32 s34, s34, s35
	v_add_u32_e32 v229, s34, v233
	global_load_dwordx4 v[34:37], v226, s[20:21] offset:0
	global_load_dwordx4 v[50:53], v227, s[6:7] offset:0
	global_load_dwordx4 v[66:69], v228, s[6:7] offset:0
	global_load_dwordx4 v[38:41], v226, s[20:21] offset:32
	global_load_dwordx4 v[54:57], v227, s[6:7] offset:32
	global_load_dwordx4 v[70:73], v228, s[6:7] offset:32
	global_load_dwordx4 v[42:45], v226, s[20:21] offset:64
	global_load_dwordx4 v[58:61], v227, s[6:7] offset:64
	global_load_dwordx4 v[74:77], v228, s[6:7] offset:64
	global_load_dwordx4 v[46:49], v226, s[20:21] offset:96
	global_load_dwordx4 v[62:65], v227, s[6:7] offset:96
	global_load_dwordx4 v[78:81], v228, s[6:7] offset:96
	global_load_dwordx4 v[82:85], v226, s[20:21] offset:128
	global_load_dwordx4 v[98:101], v227, s[6:7] offset:128
	global_load_dwordx4 v[114:117], v228, s[6:7] offset:128
	global_load_dwordx4 v[86:89], v226, s[20:21] offset:160
	global_load_dwordx4 v[102:105], v227, s[6:7] offset:160
	global_load_dwordx4 v[118:121], v228, s[6:7] offset:160
	global_load_dwordx4 v[90:93], v226, s[20:21] offset:192
	global_load_dwordx4 v[106:109], v227, s[6:7] offset:192
	global_load_dwordx4 v[122:125], v228, s[6:7] offset:192
	global_load_dwordx4 v[94:97], v226, s[20:21] offset:224
	global_load_dwordx4 v[110:113], v227, s[6:7] offset:224
	global_load_dwordx4 v[126:129], v228, s[6:7] offset:224
	global_load_dwordx4 v[130:133], v226, s[20:21] offset:256
	global_load_dwordx4 v[146:149], v227, s[6:7] offset:256
	global_load_dwordx4 v[162:165], v228, s[6:7] offset:256
	global_load_dwordx4 v[134:137], v226, s[20:21] offset:288
	global_load_dwordx4 v[150:153], v227, s[6:7] offset:288
	global_load_dwordx4 v[166:169], v228, s[6:7] offset:288
	global_load_dwordx4 v[138:141], v226, s[20:21] offset:320
	global_load_dwordx4 v[154:157], v227, s[6:7] offset:320
	global_load_dwordx4 v[170:173], v228, s[6:7] offset:320
	global_load_dwordx4 v[142:145], v226, s[20:21] offset:352
	global_load_dwordx4 v[158:161], v227, s[6:7] offset:352
	global_load_dwordx4 v[174:177], v228, s[6:7] offset:352
	global_load_dwordx4 v[178:181], v226, s[20:21] offset:384
	global_load_dwordx4 v[194:197], v227, s[6:7] offset:384
	global_load_dwordx4 v[210:213], v228, s[6:7] offset:384
	global_load_dwordx4 v[182:185], v226, s[20:21] offset:416
	global_load_dwordx4 v[198:201], v227, s[6:7] offset:416
	global_load_dwordx4 v[214:217], v228, s[6:7] offset:416
	global_load_dwordx4 v[186:189], v226, s[20:21] offset:448
	global_load_dwordx4 v[202:205], v227, s[6:7] offset:448
	global_load_dwordx4 v[218:221], v228, s[6:7] offset:448
	global_load_dwordx4 v[190:193], v226, s[20:21] offset:480
	global_load_dwordx4 v[206:209], v227, s[6:7] offset:480
	global_load_dwordx4 v[222:225], v228, s[6:7] offset:480
	s_waitcnt vmcnt(45)
	v_mfma_f32_32x32x16_bf16 v[2:17], v[34:37], v[50:53], 0
	v_mfma_f32_32x32x16_bf16 v[18:33], v[34:37], v[66:69], 0
	s_waitcnt vmcnt(42)
	v_mfma_f32_32x32x16_bf16 v[2:17], v[38:41], v[54:57], v[2:17]
	v_mfma_f32_32x32x16_bf16 v[18:33], v[38:41], v[70:73], v[18:33]
	s_waitcnt vmcnt(39)
	v_mfma_f32_32x32x16_bf16 v[2:17], v[42:45], v[58:61], v[2:17]
	v_mfma_f32_32x32x16_bf16 v[18:33], v[42:45], v[74:77], v[18:33]
	s_waitcnt vmcnt(36)
	v_mfma_f32_32x32x16_bf16 v[2:17], v[46:49], v[62:65], v[2:17]
	v_mfma_f32_32x32x16_bf16 v[18:33], v[46:49], v[78:81], v[18:33]
	global_load_dwordx4 v[34:37], v226, s[20:21] offset:512
	global_load_dwordx4 v[50:53], v227, s[6:7] offset:512
	global_load_dwordx4 v[66:69], v228, s[6:7] offset:512
	global_load_dwordx4 v[38:41], v226, s[20:21] offset:544
	global_load_dwordx4 v[54:57], v227, s[6:7] offset:544
	global_load_dwordx4 v[70:73], v228, s[6:7] offset:544
	global_load_dwordx4 v[42:45], v226, s[20:21] offset:576
	global_load_dwordx4 v[58:61], v227, s[6:7] offset:576
	global_load_dwordx4 v[74:77], v228, s[6:7] offset:576
	global_load_dwordx4 v[46:49], v226, s[20:21] offset:608
	global_load_dwordx4 v[62:65], v227, s[6:7] offset:608
	global_load_dwordx4 v[78:81], v228, s[6:7] offset:608
	s_waitcnt vmcnt(45)
	v_mfma_f32_32x32x16_bf16 v[2:17], v[82:85], v[98:101], v[2:17]
	v_mfma_f32_32x32x16_bf16 v[18:33], v[82:85], v[114:117], v[18:33]
	s_waitcnt vmcnt(42)
	v_mfma_f32_32x32x16_bf16 v[2:17], v[86:89], v[102:105], v[2:17]
	v_mfma_f32_32x32x16_bf16 v[18:33], v[86:89], v[118:121], v[18:33]
	s_waitcnt vmcnt(39)
	v_mfma_f32_32x32x16_bf16 v[2:17], v[90:93], v[106:109], v[2:17]
	v_mfma_f32_32x32x16_bf16 v[18:33], v[90:93], v[122:125], v[18:33]
	s_waitcnt vmcnt(36)
	v_mfma_f32_32x32x16_bf16 v[2:17], v[94:97], v[110:113], v[2:17]
	v_mfma_f32_32x32x16_bf16 v[18:33], v[94:97], v[126:129], v[18:33]
	global_load_dwordx4 v[82:85], v226, s[20:21] offset:640
	global_load_dwordx4 v[98:101], v227, s[6:7] offset:640
	global_load_dwordx4 v[114:117], v228, s[6:7] offset:640
	global_load_dwordx4 v[86:89], v226, s[20:21] offset:672
	global_load_dwordx4 v[102:105], v227, s[6:7] offset:672
	global_load_dwordx4 v[118:121], v228, s[6:7] offset:672
	global_load_dwordx4 v[90:93], v226, s[20:21] offset:704
	global_load_dwordx4 v[106:109], v227, s[6:7] offset:704
	global_load_dwordx4 v[122:125], v228, s[6:7] offset:704
	global_load_dwordx4 v[94:97], v226, s[20:21] offset:736
	global_load_dwordx4 v[110:113], v227, s[6:7] offset:736
	global_load_dwordx4 v[126:129], v228, s[6:7] offset:736
	s_waitcnt vmcnt(45)
	v_mfma_f32_32x32x16_bf16 v[2:17], v[130:133], v[146:149], v[2:17]
	v_mfma_f32_32x32x16_bf16 v[18:33], v[130:133], v[162:165], v[18:33]
	s_waitcnt vmcnt(42)
	v_mfma_f32_32x32x16_bf16 v[2:17], v[134:137], v[150:153], v[2:17]
	v_mfma_f32_32x32x16_bf16 v[18:33], v[134:137], v[166:169], v[18:33]
	s_waitcnt vmcnt(39)
	v_mfma_f32_32x32x16_bf16 v[2:17], v[138:141], v[154:157], v[2:17]
	v_mfma_f32_32x32x16_bf16 v[18:33], v[138:141], v[170:173], v[18:33]
	s_waitcnt vmcnt(36)
	v_mfma_f32_32x32x16_bf16 v[2:17], v[142:145], v[158:161], v[2:17]
	v_mfma_f32_32x32x16_bf16 v[18:33], v[142:145], v[174:177], v[18:33]
	global_load_dwordx4 v[130:133], v226, s[20:21] offset:768
	global_load_dwordx4 v[146:149], v227, s[6:7] offset:768
	global_load_dwordx4 v[162:165], v228, s[6:7] offset:768
	global_load_dwordx4 v[134:137], v226, s[20:21] offset:800
	global_load_dwordx4 v[150:153], v227, s[6:7] offset:800
	global_load_dwordx4 v[166:169], v228, s[6:7] offset:800
	global_load_dwordx4 v[138:141], v226, s[20:21] offset:832
	global_load_dwordx4 v[154:157], v227, s[6:7] offset:832
	global_load_dwordx4 v[170:173], v228, s[6:7] offset:832
	global_load_dwordx4 v[142:145], v226, s[20:21] offset:864
	global_load_dwordx4 v[158:161], v227, s[6:7] offset:864
	global_load_dwordx4 v[174:177], v228, s[6:7] offset:864
	s_waitcnt vmcnt(45)
	v_mfma_f32_32x32x16_bf16 v[2:17], v[178:181], v[194:197], v[2:17]
	v_mfma_f32_32x32x16_bf16 v[18:33], v[178:181], v[210:213], v[18:33]
	s_waitcnt vmcnt(42)
	v_mfma_f32_32x32x16_bf16 v[2:17], v[182:185], v[198:201], v[2:17]
	v_mfma_f32_32x32x16_bf16 v[18:33], v[182:185], v[214:217], v[18:33]
	s_waitcnt vmcnt(39)
	v_mfma_f32_32x32x16_bf16 v[2:17], v[186:189], v[202:205], v[2:17]
	v_mfma_f32_32x32x16_bf16 v[18:33], v[186:189], v[218:221], v[18:33]
	s_waitcnt vmcnt(36)
	v_mfma_f32_32x32x16_bf16 v[2:17], v[190:193], v[206:209], v[2:17]
	v_mfma_f32_32x32x16_bf16 v[18:33], v[190:193], v[222:225], v[18:33]
	global_load_dwordx4 v[178:181], v226, s[20:21] offset:896
	global_load_dwordx4 v[194:197], v227, s[6:7] offset:896
	global_load_dwordx4 v[210:213], v228, s[6:7] offset:896
	global_load_dwordx4 v[182:185], v226, s[20:21] offset:928
	global_load_dwordx4 v[198:201], v227, s[6:7] offset:928
	global_load_dwordx4 v[214:217], v228, s[6:7] offset:928
	global_load_dwordx4 v[186:189], v226, s[20:21] offset:960
	global_load_dwordx4 v[202:205], v227, s[6:7] offset:960
	global_load_dwordx4 v[218:221], v228, s[6:7] offset:960
	global_load_dwordx4 v[190:193], v226, s[20:21] offset:992
	global_load_dwordx4 v[206:209], v227, s[6:7] offset:992
	global_load_dwordx4 v[222:225], v228, s[6:7] offset:992
	s_waitcnt vmcnt(45)
	v_mfma_f32_32x32x16_bf16 v[2:17], v[34:37], v[50:53], v[2:17]
	v_mfma_f32_32x32x16_bf16 v[18:33], v[34:37], v[66:69], v[18:33]
	s_waitcnt vmcnt(42)
	v_mfma_f32_32x32x16_bf16 v[2:17], v[38:41], v[54:57], v[2:17]
	v_mfma_f32_32x32x16_bf16 v[18:33], v[38:41], v[70:73], v[18:33]
	s_waitcnt vmcnt(39)
	v_mfma_f32_32x32x16_bf16 v[2:17], v[42:45], v[58:61], v[2:17]
	v_mfma_f32_32x32x16_bf16 v[18:33], v[42:45], v[74:77], v[18:33]
	s_waitcnt vmcnt(36)
	v_mfma_f32_32x32x16_bf16 v[2:17], v[46:49], v[62:65], v[2:17]
	v_mfma_f32_32x32x16_bf16 v[18:33], v[46:49], v[78:81], v[18:33]
	s_waitcnt vmcnt(33)
	v_mfma_f32_32x32x16_bf16 v[2:17], v[82:85], v[98:101], v[2:17]
	v_mfma_f32_32x32x16_bf16 v[18:33], v[82:85], v[114:117], v[18:33]
	s_waitcnt vmcnt(30)
	v_mfma_f32_32x32x16_bf16 v[2:17], v[86:89], v[102:105], v[2:17]
	v_mfma_f32_32x32x16_bf16 v[18:33], v[86:89], v[118:121], v[18:33]
	s_waitcnt vmcnt(27)
	v_mfma_f32_32x32x16_bf16 v[2:17], v[90:93], v[106:109], v[2:17]
	v_mfma_f32_32x32x16_bf16 v[18:33], v[90:93], v[122:125], v[18:33]
	s_waitcnt vmcnt(24)
	v_mfma_f32_32x32x16_bf16 v[2:17], v[94:97], v[110:113], v[2:17]
	v_mfma_f32_32x32x16_bf16 v[18:33], v[94:97], v[126:129], v[18:33]
	s_waitcnt vmcnt(21)
	v_mfma_f32_32x32x16_bf16 v[2:17], v[130:133], v[146:149], v[2:17]
	v_mfma_f32_32x32x16_bf16 v[18:33], v[130:133], v[162:165], v[18:33]
	s_waitcnt vmcnt(18)
	v_mfma_f32_32x32x16_bf16 v[2:17], v[134:137], v[150:153], v[2:17]
	v_mfma_f32_32x32x16_bf16 v[18:33], v[134:137], v[166:169], v[18:33]
	s_waitcnt vmcnt(15)
	v_mfma_f32_32x32x16_bf16 v[2:17], v[138:141], v[154:157], v[2:17]
	v_mfma_f32_32x32x16_bf16 v[18:33], v[138:141], v[170:173], v[18:33]
	s_waitcnt vmcnt(12)
	v_mfma_f32_32x32x16_bf16 v[2:17], v[142:145], v[158:161], v[2:17]
	v_mfma_f32_32x32x16_bf16 v[18:33], v[142:145], v[174:177], v[18:33]
	s_waitcnt vmcnt(9)
	v_mfma_f32_32x32x16_bf16 v[2:17], v[178:181], v[194:197], v[2:17]
	v_mfma_f32_32x32x16_bf16 v[18:33], v[178:181], v[210:213], v[18:33]
	s_waitcnt vmcnt(6)
	v_mfma_f32_32x32x16_bf16 v[2:17], v[182:185], v[198:201], v[2:17]
	v_mfma_f32_32x32x16_bf16 v[18:33], v[182:185], v[214:217], v[18:33]
	s_waitcnt vmcnt(3)
	v_mfma_f32_32x32x16_bf16 v[2:17], v[186:189], v[202:205], v[2:17]
	v_mfma_f32_32x32x16_bf16 v[18:33], v[186:189], v[218:221], v[18:33]
	s_waitcnt vmcnt(0)
	v_mfma_f32_32x32x16_bf16 v[2:17], v[190:193], v[206:209], v[2:17]
	v_mfma_f32_32x32x16_bf16 v[18:33], v[190:193], v[222:225], v[18:33]
	s_nop 15
	s_nop 3
	global_store_dword v229, v2, s[22:23]
	global_store_dword v229, v18, s[22:23] offset:128
	v_add_u32_e32 v231, 0x1000, v229
	global_store_dword v231, v3, s[22:23]
	global_store_dword v231, v19, s[22:23] offset:128
	v_add_u32_e32 v230, 0x2000, v229
	global_store_dword v230, v4, s[22:23]
	global_store_dword v230, v20, s[22:23] offset:128
	v_add_u32_e32 v231, 0x3000, v229
	global_store_dword v231, v5, s[22:23]
	global_store_dword v231, v21, s[22:23] offset:128
	v_add_u32_e32 v230, 0x8000, v229
	global_store_dword v230, v6, s[22:23]
	global_store_dword v230, v22, s[22:23] offset:128
	v_add_u32_e32 v231, 0x9000, v229
	global_store_dword v231, v7, s[22:23]
	global_store_dword v231, v23, s[22:23] offset:128
	v_add_u32_e32 v230, 0xa000, v229
	global_store_dword v230, v8, s[22:23]
	global_store_dword v230, v24, s[22:23] offset:128
	v_add_u32_e32 v231, 0xb000, v229
	global_store_dword v231, v9, s[22:23]
	global_store_dword v231, v25, s[22:23] offset:128
	v_add_u32_e32 v230, 0x10000, v229
	global_store_dword v230, v10, s[22:23]
	global_store_dword v230, v26, s[22:23] offset:128
	v_add_u32_e32 v231, 0x11000, v229
	global_store_dword v231, v11, s[22:23]
	global_store_dword v231, v27, s[22:23] offset:128
	v_add_u32_e32 v230, 0x12000, v229
	global_store_dword v230, v12, s[22:23]
	global_store_dword v230, v28, s[22:23] offset:128
	v_add_u32_e32 v231, 0x13000, v229
	global_store_dword v231, v13, s[22:23]
	global_store_dword v231, v29, s[22:23] offset:128
	v_add_u32_e32 v230, 0x18000, v229
	global_store_dword v230, v14, s[22:23]
	global_store_dword v230, v30, s[22:23] offset:128
	v_add_u32_e32 v231, 0x19000, v229
	global_store_dword v231, v15, s[22:23]
	global_store_dword v231, v31, s[22:23] offset:128
	v_add_u32_e32 v230, 0x1a000, v229
	global_store_dword v230, v16, s[22:23]
	global_store_dword v230, v32, s[22:23] offset:128
	v_add_u32_e32 v231, 0x1b000, v229
	global_store_dword v231, v17, s[22:23]
	global_store_dword v231, v33, s[22:23] offset:128
	s_add_i32 s12, s12, s24
	s_cmpk_lt_i32 s12, 0x200
	s_cbranch_scc1 .Lsg3_unit

	.amdhsa_kernel _Z10fwd_kernelILi3ELi4EEv4Args
		.amdhsa_group_segment_fixed_size 0
		.amdhsa_private_segment_fixed_size 0
		.amdhsa_kernarg_size 488
		.amdhsa_user_sgpr_count 2
		.amdhsa_user_sgpr_dispatch_ptr 0
		.amdhsa_user_sgpr_queue_ptr 0
		.amdhsa_user_sgpr_kernarg_segment_ptr 1
		.amdhsa_user_sgpr_dispatch_id 0
		.amdhsa_user_sgpr_kernarg_preload_length 0
		.amdhsa_user_sgpr_kernarg_preload_offset 0
		.amdhsa_user_sgpr_private_segment_size 0
		.amdhsa_uses_dynamic_stack 0
		.amdhsa_enable_private_segment 0
		.amdhsa_system_sgpr_workgroup_id_x 1
		.amdhsa_system_sgpr_workgroup_id_y 0
		.amdhsa_system_sgpr_workgroup_id_z 0
		.amdhsa_system_sgpr_workgroup_info 0
		.amdhsa_system_vgpr_workitem_id 0
		.amdhsa_next_free_vgpr 240
		.amdhsa_next_free_sgpr 61
		.amdhsa_accum_offset 240
		.amdhsa_reserve_vcc 1
		.amdhsa_float_round_mode_32 0
		.amdhsa_float_round_mode_16_64 0
		.amdhsa_float_denorm_mode_32 3
		.amdhsa_float_denorm_mode_16_64 3
		.amdhsa_dx10_clamp 1
		.amdhsa_ieee_mode 1
		.amdhsa_fp16_overflow 0
		.amdhsa_tg_split 0
		.amdhsa_exception_fp_ieee_invalid_op 0
		.amdhsa_exception_fp_denorm_src 0
		.amdhsa_exception_fp_ieee_div_zero 0
		.amdhsa_exception_fp_ieee_overflow 0
		.amdhsa_exception_fp_ieee_underflow 0
		.amdhsa_exception_fp_ieee_inexact 0
		.amdhsa_exception_int_div_zero 0
	.end_amdhsa_kernel

_Z10fwd_kernelILi6ELi7EEv4Args:
	v_mov_b32_e32 v1, v0
	s_load_dword s3, s[0:1], 0xe8
	s_load_dwordx2 s[0:1], s[0:1], 0xd8
	v_readfirstlane_b32 s4, v1
	s_ashr_i32 s4, s4, 6
	s_waitcnt lgkmcnt(0)
	s_add_u32 s6, s0, 0x1100000
	s_addc_u32 s7, s1, 0
	s_lshl_b32 s5, s2, 3
	s_add_i32 s14, s5, s4
	s_cmpk_gt_i32 s14, 0x7ff
	s_cbranch_scc1 .LBB6_3
	s_add_u32 s20, s0, 0xf400000
	s_addc_u32 s21, s1, 0
	s_add_u32 s22, s0, 0x100000
	s_addc_u32 s23, s1, 0
	s_lshl_b32 s24, s3, 3
	v_and_b32_e32 v234, 31, v0
	v_bfe_u32 v235, v0, 5, 1
	v_lshlrev_b32_e32 v232, 13, v234
	v_lshl_add_u32 v232, v235, 4, v232
	v_lshlrev_b32_e32 v233, 2, v234
	v_lshl_add_u32 v233, v235, 14, v233
.Lsg6_unit:
	s_and_b32 s28, s14, 7
	s_lshr_b32 s29, s14, 3
	s_bfe_u32 s25, s29, 0x30001
	s_lshr_b32 s26, s29, 4
	s_and_b32 s27, s29, 1
	s_lshl_b32 s27, s27, 3
	s_add_u32 s27, s27, s28
	s_lshl_b32 s30, s25, 10
	s_lshl_b32 s31, s27, 18
	s_add_u32 s31, s31, s30
	s_lshl_b32 s33, s26, 19
	s_add_u32 s33, s33, s30
	v_add_u32_e32 v226, s31, v232
	v_add_u32_e32 v227, s33, v232
	v_add_u32_e32 v228, 0x40000, v227
	s_lshl_b32 s34, s25, 21
	s_lshl_b32 s35, s27, 17
	s_add_u32 s34, s34, s35
	s_lshl_b32 s35, s26, 8
	s_add_u32 s34, s34, s35
	v_add_u32_e32 v229, s34, v233
	global_load_dwordx4 v[34:37], v226, s[20:21] offset:0
	global_load_dwordx4 v[50:53], v227, s[6:7] offset:0
	global_load_dwordx4 v[66:69], v228, s[6:7] offset:0
	global_load_dwordx4 v[38:41], v226, s[20:21] offset:32
	global_load_dwordx4 v[54:57], v227, s[6:7] offset:32
	global_load_dwordx4 v[70:73], v228, s[6:7] offset:32
	global_load_dwordx4 v[42:45], v226, s[20:21] offset:64
	global_load_dwordx4 v[58:61], v227, s[6:7] offset:64
	global_load_dwordx4 v[74:77], v228, s[6:7] offset:64
	global_load_dwordx4 v[46:49], v226, s[20:21] offset:96
	global_load_dwordx4 v[62:65], v227, s[6:7] offset:96
	global_load_dwordx4 v[78:81], v228, s[6:7] offset:96
	global_load_dwordx4 v[82:85], v226, s[20:21] offset:128
	global_load_dwordx4 v[98:101], v227, s[6:7] offset:128
	global_load_dwordx4 v[114:117], v228, s[6:7] offset:128
	global_load_dwordx4 v[86:89], v226, s[20:21] offset:160
	global_load_dwordx4 v[102:105], v227, s[6:7] offset:160
	global_load_dwordx4 v[118:121], v228, s[6:7] offset:160
	global_load_dwordx4 v[90:93], v226, s[20:21] offset:192
	global_load_dwordx4 v[106:109], v227, s[6:7] offset:192
	global_load_dwordx4 v[122:125], v228, s[6:7] offset:192
	global_load_dwordx4 v[94:97], v226, s[20:21] offset:224
	global_load_dwordx4 v[110:113], v227, s[6:7] offset:224
	global_load_dwordx4 v[126:129], v228, s[6:7] offset:224
	global_load_dwordx4 v[130:133], v226, s[20:21] offset:256
	global_load_dwordx4 v[146:149], v227, s[6:7] offset:256
	global_load_dwordx4 v[162:165], v228, s[6:7] offset:256
	global_load_dwordx4 v[134:137], v226, s[20:21] offset:288
	global_load_dwordx4 v[150:153], v227, s[6:7] offset:288
	global_load_dwordx4 v[166:169], v228, s[6:7] offset:288
	global_load_dwordx4 v[138:141], v226, s[20:21] offset:320
	global_load_dwordx4 v[154:157], v227, s[6:7] offset:320
	global_load_dwordx4 v[170:173], v228, s[6:7] offset:320
	global_load_dwordx4 v[142:145], v226, s[20:21] offset:352
	global_load_dwordx4 v[158:161], v227, s[6:7] offset:352
	global_load_dwordx4 v[174:177], v228, s[6:7] offset:352
	global_load_dwordx4 v[178:181], v226, s[20:21] offset:384
	global_load_dwordx4 v[194:197], v227, s[6:7] offset:384
	global_load_dwordx4 v[210:213], v228, s[6:7] offset:384
	global_load_dwordx4 v[182:185], v226, s[20:21] offset:416
	global_load_dwordx4 v[198:201], v227, s[6:7] offset:416
	global_load_dwordx4 v[214:217], v228, s[6:7] offset:416
	global_load_dwordx4 v[186:189], v226, s[20:21] offset:448
	global_load_dwordx4 v[202:205], v227, s[6:7] offset:448
	global_load_dwordx4 v[218:221], v228, s[6:7] offset:448
	global_load_dwordx4 v[190:193], v226, s[20:21] offset:480
	global_load_dwordx4 v[206:209], v227, s[6:7] offset:480
	global_load_dwordx4 v[222:225], v228, s[6:7] offset:480
	s_waitcnt vmcnt(45)
	v_mfma_f32_32x32x16_bf16 v[2:17], v[34:37], v[50:53], 0
	v_mfma_f32_32x32x16_bf16 v[18:33], v[34:37], v[66:69], 0
	s_waitcnt vmcnt(42)
	v_mfma_f32_32x32x16_bf16 v[2:17], v[38:41], v[54:57], v[2:17]
	v_mfma_f32_32x32x16_bf16 v[18:33], v[38:41], v[70:73], v[18:33]
	s_waitcnt vmcnt(39)
	v_mfma_f32_32x32x16_bf16 v[2:17], v[42:45], v[58:61], v[2:17]
	v_mfma_f32_32x32x16_bf16 v[18:33], v[42:45], v[74:77], v[18:33]
	s_waitcnt vmcnt(36)
	v_mfma_f32_32x32x16_bf16 v[2:17], v[46:49], v[62:65], v[2:17]
	v_mfma_f32_32x32x16_bf16 v[18:33], v[46:49], v[78:81], v[18:33]
	global_load_dwordx4 v[34:37], v226, s[20:21] offset:512
	global_load_dwordx4 v[50:53], v227, s[6:7] offset:512
	global_load_dwordx4 v[66:69], v228, s[6:7] offset:512
	global_load_dwordx4 v[38:41], v226, s[20:21] offset:544
	global_load_dwordx4 v[54:57], v227, s[6:7] offset:544
	global_load_dwordx4 v[70:73], v228, s[6:7] offset:544
	global_load_dwordx4 v[42:45], v226, s[20:21] offset:576
	global_load_dwordx4 v[58:61], v227, s[6:7] offset:576
	global_load_dwordx4 v[74:77], v228, s[6:7] offset:576
	global_load_dwordx4 v[46:49], v226, s[20:21] offset:608
	global_load_dwordx4 v[62:65], v227, s[6:7] offset:608
	global_load_dwordx4 v[78:81], v228, s[6:7] offset:608
	s_waitcnt vmcnt(45)
	v_mfma_f32_32x32x16_bf16 v[2:17], v[82:85], v[98:101], v[2:17]
	v_mfma_f32_32x32x16_bf16 v[18:33], v[82:85], v[114:117], v[18:33]
	s_waitcnt vmcnt(42)
	v_mfma_f32_32x32x16_bf16 v[2:17], v[86:89], v[102:105], v[2:17]
	v_mfma_f32_32x32x16_bf16 v[18:33], v[86:89], v[118:121], v[18:33]
	s_waitcnt vmcnt(39)
	v_mfma_f32_32x32x16_bf16 v[2:17], v[90:93], v[106:109], v[2:17]
	v_mfma_f32_32x32x16_bf16 v[18:33], v[90:93], v[122:125], v[18:33]
	s_waitcnt vmcnt(36)
	v_mfma_f32_32x32x16_bf16 v[2:17], v[94:97], v[110:113], v[2:17]
	v_mfma_f32_32x32x16_bf16 v[18:33], v[94:97], v[126:129], v[18:33]
	global_load_dwordx4 v[82:85], v226, s[20:21] offset:640
	global_load_dwordx4 v[98:101], v227, s[6:7] offset:640
	global_load_dwordx4 v[114:117], v228, s[6:7] offset:640
	global_load_dwordx4 v[86:89], v226, s[20:21] offset:672
	global_load_dwordx4 v[102:105], v227, s[6:7] offset:672
	global_load_dwordx4 v[118:121], v228, s[6:7] offset:672
	global_load_dwordx4 v[90:93], v226, s[20:21] offset:704
	global_load_dwordx4 v[106:109], v227, s[6:7] offset:704
	global_load_dwordx4 v[122:125], v228, s[6:7] offset:704
	global_load_dwordx4 v[94:97], v226, s[20:21] offset:736
	global_load_dwordx4 v[110:113], v227, s[6:7] offset:736
	global_load_dwordx4 v[126:129], v228, s[6:7] offset:736
	s_waitcnt vmcnt(45)
	v_mfma_f32_32x32x16_bf16 v[2:17], v[130:133], v[146:149], v[2:17]
	v_mfma_f32_32x32x16_bf16 v[18:33], v[130:133], v[162:165], v[18:33]
	s_waitcnt vmcnt(42)
	v_mfma_f32_32x32x16_bf16 v[2:17], v[134:137], v[150:153], v[2:17]
	v_mfma_f32_32x32x16_bf16 v[18:33], v[134:137], v[166:169], v[18:33]
	s_waitcnt vmcnt(39)
	v_mfma_f32_32x32x16_bf16 v[2:17], v[138:141], v[154:157], v[2:17]
	v_mfma_f32_32x32x16_bf16 v[18:33], v[138:141], v[170:173], v[18:33]
	s_waitcnt vmcnt(36)
	v_mfma_f32_32x32x16_bf16 v[2:17], v[142:145], v[158:161], v[2:17]
	v_mfma_f32_32x32x16_bf16 v[18:33], v[142:145], v[174:177], v[18:33]
	global_load_dwordx4 v[130:133], v226, s[20:21] offset:768
	global_load_dwordx4 v[146:149], v227, s[6:7] offset:768
	global_load_dwordx4 v[162:165], v228, s[6:7] offset:768
	global_load_dwordx4 v[134:137], v226, s[20:21] offset:800
	global_load_dwordx4 v[150:153], v227, s[6:7] offset:800
	global_load_dwordx4 v[166:169], v228, s[6:7] offset:800
	global_load_dwordx4 v[138:141], v226, s[20:21] offset:832
	global_load_dwordx4 v[154:157], v227, s[6:7] offset:832
	global_load_dwordx4 v[170:173], v228, s[6:7] offset:832
	global_load_dwordx4 v[142:145], v226, s[20:21] offset:864
	global_load_dwordx4 v[158:161], v227, s[6:7] offset:864
	global_load_dwordx4 v[174:177], v228, s[6:7] offset:864
	s_waitcnt vmcnt(45)
	v_mfma_f32_32x32x16_bf16 v[2:17], v[178:181], v[194:197], v[2:17]
	v_mfma_f32_32x32x16_bf16 v[18:33], v[178:181], v[210:213], v[18:33]
	s_waitcnt vmcnt(42)
	v_mfma_f32_32x32x16_bf16 v[2:17], v[182:185], v[198:201], v[2:17]
	v_mfma_f32_32x32x16_bf16 v[18:33], v[182:185], v[214:217], v[18:33]
	s_waitcnt vmcnt(39)
	v_mfma_f32_32x32x16_bf16 v[2:17], v[186:189], v[202:205], v[2:17]
	v_mfma_f32_32x32x16_bf16 v[18:33], v[186:189], v[218:221], v[18:33]
	s_waitcnt vmcnt(36)
	v_mfma_f32_32x32x16_bf16 v[2:17], v[190:193], v[206:209], v[2:17]
	v_mfma_f32_32x32x16_bf16 v[18:33], v[190:193], v[222:225], v[18:33]
	global_load_dwordx4 v[178:181], v226, s[20:21] offset:896
	global_load_dwordx4 v[194:197], v227, s[6:7] offset:896
	global_load_dwordx4 v[210:213], v228, s[6:7] offset:896
	global_load_dwordx4 v[182:185], v226, s[20:21] offset:928
	global_load_dwordx4 v[198:201], v227, s[6:7] offset:928
	global_load_dwordx4 v[214:217], v228, s[6:7] offset:928
	global_load_dwordx4 v[186:189], v226, s[20:21] offset:960
	global_load_dwordx4 v[202:205], v227, s[6:7] offset:960
	global_load_dwordx4 v[218:221], v228, s[6:7] offset:960
	global_load_dwordx4 v[190:193], v226, s[20:21] offset:992
	global_load_dwordx4 v[206:209], v227, s[6:7] offset:992
	global_load_dwordx4 v[222:225], v228, s[6:7] offset:992
	s_waitcnt vmcnt(45)
	v_mfma_f32_32x32x16_bf16 v[2:17], v[34:37], v[50:53], v[2:17]
	v_mfma_f32_32x32x16_bf16 v[18:33], v[34:37], v[66:69], v[18:33]
	s_waitcnt vmcnt(42)
	v_mfma_f32_32x32x16_bf16 v[2:17], v[38:41], v[54:57], v[2:17]
	v_mfma_f32_32x32x16_bf16 v[18:33], v[38:41], v[70:73], v[18:33]
	s_waitcnt vmcnt(39)
	v_mfma_f32_32x32x16_bf16 v[2:17], v[42:45], v[58:61], v[2:17]
	v_mfma_f32_32x32x16_bf16 v[18:33], v[42:45], v[74:77], v[18:33]
	s_waitcnt vmcnt(36)
	v_mfma_f32_32x32x16_bf16 v[2:17], v[46:49], v[62:65], v[2:17]
	v_mfma_f32_32x32x16_bf16 v[18:33], v[46:49], v[78:81], v[18:33]
	s_waitcnt vmcnt(33)
	v_mfma_f32_32x32x16_bf16 v[2:17], v[82:85], v[98:101], v[2:17]
	v_mfma_f32_32x32x16_bf16 v[18:33], v[82:85], v[114:117], v[18:33]
	s_waitcnt vmcnt(30)
	v_mfma_f32_32x32x16_bf16 v[2:17], v[86:89], v[102:105], v[2:17]
	v_mfma_f32_32x32x16_bf16 v[18:33], v[86:89], v[118:121], v[18:33]
	s_waitcnt vmcnt(27)
	v_mfma_f32_32x32x16_bf16 v[2:17], v[90:93], v[106:109], v[2:17]
	v_mfma_f32_32x32x16_bf16 v[18:33], v[90:93], v[122:125], v[18:33]
	s_waitcnt vmcnt(24)
	v_mfma_f32_32x32x16_bf16 v[2:17], v[94:97], v[110:113], v[2:17]
	v_mfma_f32_32x32x16_bf16 v[18:33], v[94:97], v[126:129], v[18:33]
	s_waitcnt vmcnt(21)
	v_mfma_f32_32x32x16_bf16 v[2:17], v[130:133], v[146:149], v[2:17]
	v_mfma_f32_32x32x16_bf16 v[18:33], v[130:133], v[162:165], v[18:33]
	s_waitcnt vmcnt(18)
	v_mfma_f32_32x32x16_bf16 v[2:17], v[134:137], v[150:153], v[2:17]
	v_mfma_f32_32x32x16_bf16 v[18:33], v[134:137], v[166:169], v[18:33]
	s_waitcnt vmcnt(15)
	v_mfma_f32_32x32x16_bf16 v[2:17], v[138:141], v[154:157], v[2:17]
	v_mfma_f32_32x32x16_bf16 v[18:33], v[138:141], v[170:173], v[18:33]
	s_waitcnt vmcnt(12)
	v_mfma_f32_32x32x16_bf16 v[2:17], v[142:145], v[158:161], v[2:17]
	v_mfma_f32_32x32x16_bf16 v[18:33], v[142:145], v[174:177], v[18:33]
	s_waitcnt vmcnt(9)
	v_mfma_f32_32x32x16_bf16 v[2:17], v[178:181], v[194:197], v[2:17]
	v_mfma_f32_32x32x16_bf16 v[18:33], v[178:181], v[210:213], v[18:33]
	s_waitcnt vmcnt(6)
	v_mfma_f32_32x32x16_bf16 v[2:17], v[182:185], v[198:201], v[2:17]
	v_mfma_f32_32x32x16_bf16 v[18:33], v[182:185], v[214:217], v[18:33]
	s_waitcnt vmcnt(3)
	v_mfma_f32_32x32x16_bf16 v[2:17], v[186:189], v[202:205], v[2:17]
	v_mfma_f32_32x32x16_bf16 v[18:33], v[186:189], v[218:221], v[18:33]
	s_waitcnt vmcnt(0)
	v_mfma_f32_32x32x16_bf16 v[2:17], v[190:193], v[206:209], v[2:17]
	v_mfma_f32_32x32x16_bf16 v[18:33], v[190:193], v[222:225], v[18:33]
	s_nop 15
	s_nop 3
	global_store_dword v229, v2, s[22:23]
	global_store_dword v229, v18, s[22:23] offset:128
	v_add_u32_e32 v231, 0x1000, v229
	global_store_dword v231, v3, s[22:23]
	global_store_dword v231, v19, s[22:23] offset:128
	v_add_u32_e32 v230, 0x2000, v229
	global_store_dword v230, v4, s[22:23]
	global_store_dword v230, v20, s[22:23] offset:128
	v_add_u32_e32 v231, 0x3000, v229
	global_store_dword v231, v5, s[22:23]
	global_store_dword v231, v21, s[22:23] offset:128
	v_add_u32_e32 v230, 0x8000, v229
	global_store_dword v230, v6, s[22:23]
	global_store_dword v230, v22, s[22:23] offset:128
	v_add_u32_e32 v231, 0x9000, v229
	global_store_dword v231, v7, s[22:23]
	global_store_dword v231, v23, s[22:23] offset:128
	v_add_u32_e32 v230, 0xa000, v229
	global_store_dword v230, v8, s[22:23]
	global_store_dword v230, v24, s[22:23] offset:128
	v_add_u32_e32 v231, 0xb000, v229
	global_store_dword v231, v9, s[22:23]
	global_store_dword v231, v25, s[22:23] offset:128
	v_add_u32_e32 v230, 0x10000, v229
	global_store_dword v230, v10, s[22:23]
	global_store_dword v230, v26, s[22:23] offset:128
	v_add_u32_e32 v231, 0x11000, v229
	global_store_dword v231, v11, s[22:23]
	global_store_dword v231, v27, s[22:23] offset:128
	v_add_u32_e32 v230, 0x12000, v229
	global_store_dword v230, v12, s[22:23]
	global_store_dword v230, v28, s[22:23] offset:128
	v_add_u32_e32 v231, 0x13000, v229
	global_store_dword v231, v13, s[22:23]
	global_store_dword v231, v29, s[22:23] offset:128
	v_add_u32_e32 v230, 0x18000, v229
	global_store_dword v230, v14, s[22:23]
	global_store_dword v230, v30, s[22:23] offset:128
	v_add_u32_e32 v231, 0x19000, v229
	global_store_dword v231, v15, s[22:23]
	global_store_dword v231, v31, s[22:23] offset:128
	v_add_u32_e32 v230, 0x1a000, v229
	global_store_dword v230, v16, s[22:23]
	global_store_dword v230, v32, s[22:23] offset:128
	v_add_u32_e32 v231, 0x1b000, v229
	global_store_dword v231, v17, s[22:23]
	global_store_dword v231, v33, s[22:23] offset:128
	s_add_i32 s14, s14, s24
	s_cmpk_lt_i32 s14, 0x800
	s_cbranch_scc1 .Lsg6_unit

	.amdhsa_kernel _Z10fwd_kernelILi6ELi7EEv4Args
		.amdhsa_group_segment_fixed_size 0
		.amdhsa_private_segment_fixed_size 0
		.amdhsa_kernarg_size 488
		.amdhsa_user_sgpr_count 2
		.amdhsa_user_sgpr_dispatch_ptr 0
		.amdhsa_user_sgpr_queue_ptr 0
		.amdhsa_user_sgpr_kernarg_segment_ptr 1
		.amdhsa_user_sgpr_dispatch_id 0
		.amdhsa_user_sgpr_kernarg_preload_length 0
		.amdhsa_user_sgpr_kernarg_preload_offset 0
		.amdhsa_user_sgpr_private_segment_size 0
		.amdhsa_uses_dynamic_stack 0
		.amdhsa_enable_private_segment 0
		.amdhsa_system_sgpr_workgroup_id_x 1
		.amdhsa_system_sgpr_workgroup_id_y 0
		.amdhsa_system_sgpr_workgroup_id_z 0
		.amdhsa_system_sgpr_workgroup_info 0
		.amdhsa_system_vgpr_workitem_id 0
		.amdhsa_next_free_vgpr 240
		.amdhsa_next_free_sgpr 61
		.amdhsa_accum_offset 240
		.amdhsa_reserve_vcc 1
		.amdhsa_float_round_mode_32 0
		.amdhsa_float_round_mode_16_64 0
		.amdhsa_float_denorm_mode_32 3
		.amdhsa_float_denorm_mode_16_64 3
		.amdhsa_dx10_clamp 1
		.amdhsa_ieee_mode 1
		.amdhsa_fp16_overflow 0
		.amdhsa_tg_split 0
		.amdhsa_exception_fp_ieee_invalid_op 0
		.amdhsa_exception_fp_denorm_src 0
		.amdhsa_exception_fp_ieee_div_zero 0
		.amdhsa_exception_fp_ieee_overflow 0
		.amdhsa_exception_fp_ieee_underflow 0
		.amdhsa_exception_fp_ieee_inexact 0
		.amdhsa_exception_int_div_zero 0
	.end_amdhsa_kernel

_Z10fwd_kernelILi10ELi11EEv4Args:
	v_mov_b32_e32 v1, v0
	s_load_dword s3, s[0:1], 0xe8
	s_load_dwordx2 s[0:1], s[0:1], 0xd8
	v_readfirstlane_b32 s4, v1
	s_ashr_i32 s6, s4, 6
	s_waitcnt lgkmcnt(0)
	s_add_u32 s4, s0, 0x1f00000
	s_addc_u32 s5, s1, 0
	s_mul_i32 s7, s6, s3
	s_add_i32 s12, s7, s2
	s_cmpk_gt_i32 s12, 0x1ff
	s_cbranch_scc1 .LBB10_3
	s_add_u32 s20, s0, 0xf700000
	s_addc_u32 s21, s1, 0
	s_add_u32 s22, s0, 0x7400000
	s_addc_u32 s23, s1, 0
	s_lshl_b32 s24, s3, 3
	v_and_b32_e32 v234, 31, v0
	v_bfe_u32 v235, v0, 5, 1
	v_lshlrev_b32_e32 v232, 11, v234
	v_lshl_add_u32 v232, v235, 4, v232
	v_lshlrev_b32_e32 v233, 2, v234
	v_lshl_add_u32 v233, v235, 14, v233
.Lsg10_unit:
	s_and_b32 s28, s12, 0xff
	s_lshr_b32 s29, s12, 8
	s_lshr_b32 s26, s28, 4
	s_bfe_u32 s25, s28, 0x10003
	s_and_b32 s27, s28, 7
	s_lshl_b32 s29, s29, 3
	s_add_u32 s27, s27, s29
	s_lshl_b32 s30, s25, 10
	s_lshl_b32 s31, s27, 16
	s_add_u32 s31, s31, s30
	s_lshl_b32 s33, s26, 17
	s_add_u32 s33, s33, s30
	v_add_u32_e32 v226, s31, v232
	v_add_u32_e32 v227, s33, v232
	v_add_u32_e32 v228, 0x10000, v227
	s_lshl_b32 s34, s25, 21
	s_lshl_b32 s35, s27, 17
	s_add_u32 s34, s34, s35
	s_lshl_b32 s35, s26, 8
	s_add_u32 s34, s34, s35
	v_add_u32_e32 v229, s34, v233
	global_load_dwordx4 v[34:37], v226, s[20:21] offset:0
	global_load_dwordx4 v[50:53], v227, s[4:5] offset:0
	global_load_dwordx4 v[66:69], v228, s[4:5] offset:0
	global_load_dwordx4 v[38:41], v226, s[20:21] offset:32
	global_load_dwordx4 v[54:57], v227, s[4:5] offset:32
	global_load_dwordx4 v[70:73], v228, s[4:5] offset:32
	global_load_dwordx4 v[42:45], v226, s[20:21] offset:64
	global_load_dwordx4 v[58:61], v227, s[4:5] offset:64
	global_load_dwordx4 v[74:77], v228, s[4:5] offset:64
	global_load_dwordx4 v[46:49], v226, s[20:21] offset:96
	global_load_dwordx4 v[62:65], v227, s[4:5] offset:96
	global_load_dwordx4 v[78:81], v228, s[4:5] offset:96
	global_load_dwordx4 v[82:85], v226, s[20:21] offset:128
	global_load_dwordx4 v[98:101], v227, s[4:5] offset:128
	global_load_dwordx4 v[114:117], v228, s[4:5] offset:128
	global_load_dwordx4 v[86:89], v226, s[20:21] offset:160
	global_load_dwordx4 v[102:105], v227, s[4:5] offset:160
	global_load_dwordx4 v[118:121], v228, s[4:5] offset:160
	global_load_dwordx4 v[90:93], v226, s[20:21] offset:192
	global_load_dwordx4 v[106:109], v227, s[4:5] offset:192
	global_load_dwordx4 v[122:125], v228, s[4:5] offset:192
	global_load_dwordx4 v[94:97], v226, s[20:21] offset:224
	global_load_dwordx4 v[110:113], v227, s[4:5] offset:224
	global_load_dwordx4 v[126:129], v228, s[4:5] offset:224
	global_load_dwordx4 v[130:133], v226, s[20:21] offset:256
	global_load_dwordx4 v[146:149], v227, s[4:5] offset:256
	global_load_dwordx4 v[162:165], v228, s[4:5] offset:256
	global_load_dwordx4 v[134:137], v226, s[20:21] offset:288
	global_load_dwordx4 v[150:153], v227, s[4:5] offset:288
	global_load_dwordx4 v[166:169], v228, s[4:5] offset:288
	global_load_dwordx4 v[138:141], v226, s[20:21] offset:320
	global_load_dwordx4 v[154:157], v227, s[4:5] offset:320
	global_load_dwordx4 v[170:173], v228, s[4:5] offset:320
	global_load_dwordx4 v[142:145], v226, s[20:21] offset:352
	global_load_dwordx4 v[158:161], v227, s[4:5] offset:352
	global_load_dwordx4 v[174:177], v228, s[4:5] offset:352
	global_load_dwordx4 v[178:181], v226, s[20:21] offset:384
	global_load_dwordx4 v[194:197], v227, s[4:5] offset:384
	global_load_dwordx4 v[210:213], v228, s[4:5] offset:384
	global_load_dwordx4 v[182:185], v226, s[20:21] offset:416
	global_load_dwordx4 v[198:201], v227, s[4:5] offset:416
	global_load_dwordx4 v[214:217], v228, s[4:5] offset:416
	global_load_dwordx4 v[186:189], v226, s[20:21] offset:448
	global_load_dwordx4 v[202:205], v227, s[4:5] offset:448
	global_load_dwordx4 v[218:221], v228, s[4:5] offset:448
	global_load_dwordx4 v[190:193], v226, s[20:21] offset:480
	global_load_dwordx4 v[206:209], v227, s[4:5] offset:480
	global_load_dwordx4 v[222:225], v228, s[4:5] offset:480
	s_waitcnt vmcnt(45)
	v_mfma_f32_32x32x16_bf16 v[2:17], v[34:37], v[50:53], 0
	v_mfma_f32_32x32x16_bf16 v[18:33], v[34:37], v[66:69], 0
	s_waitcnt vmcnt(42)
	v_mfma_f32_32x32x16_bf16 v[2:17], v[38:41], v[54:57], v[2:17]
	v_mfma_f32_32x32x16_bf16 v[18:33], v[38:41], v[70:73], v[18:33]
	s_waitcnt vmcnt(39)
	v_mfma_f32_32x32x16_bf16 v[2:17], v[42:45], v[58:61], v[2:17]
	v_mfma_f32_32x32x16_bf16 v[18:33], v[42:45], v[74:77], v[18:33]
	s_waitcnt vmcnt(36)
	v_mfma_f32_32x32x16_bf16 v[2:17], v[46:49], v[62:65], v[2:17]
	v_mfma_f32_32x32x16_bf16 v[18:33], v[46:49], v[78:81], v[18:33]
	global_load_dwordx4 v[34:37], v226, s[20:21] offset:512
	global_load_dwordx4 v[50:53], v227, s[4:5] offset:512
	global_load_dwordx4 v[66:69], v228, s[4:5] offset:512
	global_load_dwordx4 v[38:41], v226, s[20:21] offset:544
	global_load_dwordx4 v[54:57], v227, s[4:5] offset:544
	global_load_dwordx4 v[70:73], v228, s[4:5] offset:544
	global_load_dwordx4 v[42:45], v226, s[20:21] offset:576
	global_load_dwordx4 v[58:61], v227, s[4:5] offset:576
	global_load_dwordx4 v[74:77], v228, s[4:5] offset:576
	global_load_dwordx4 v[46:49], v226, s[20:21] offset:608
	global_load_dwordx4 v[62:65], v227, s[4:5] offset:608
	global_load_dwordx4 v[78:81], v228, s[4:5] offset:608
	s_waitcnt vmcnt(45)
	v_mfma_f32_32x32x16_bf16 v[2:17], v[82:85], v[98:101], v[2:17]
	v_mfma_f32_32x32x16_bf16 v[18:33], v[82:85], v[114:117], v[18:33]
	s_waitcnt vmcnt(42)
	v_mfma_f32_32x32x16_bf16 v[2:17], v[86:89], v[102:105], v[2:17]
	v_mfma_f32_32x32x16_bf16 v[18:33], v[86:89], v[118:121], v[18:33]
	s_waitcnt vmcnt(39)
	v_mfma_f32_32x32x16_bf16 v[2:17], v[90:93], v[106:109], v[2:17]
	v_mfma_f32_32x32x16_bf16 v[18:33], v[90:93], v[122:125], v[18:33]
	s_waitcnt vmcnt(36)
	v_mfma_f32_32x32x16_bf16 v[2:17], v[94:97], v[110:113], v[2:17]
	v_mfma_f32_32x32x16_bf16 v[18:33], v[94:97], v[126:129], v[18:33]
	global_load_dwordx4 v[82:85], v226, s[20:21] offset:640
	global_load_dwordx4 v[98:101], v227, s[4:5] offset:640
	global_load_dwordx4 v[114:117], v228, s[4:5] offset:640
	global_load_dwordx4 v[86:89], v226, s[20:21] offset:672
	global_load_dwordx4 v[102:105], v227, s[4:5] offset:672
	global_load_dwordx4 v[118:121], v228, s[4:5] offset:672
	global_load_dwordx4 v[90:93], v226, s[20:21] offset:704
	global_load_dwordx4 v[106:109], v227, s[4:5] offset:704
	global_load_dwordx4 v[122:125], v228, s[4:5] offset:704
	global_load_dwordx4 v[94:97], v226, s[20:21] offset:736
	global_load_dwordx4 v[110:113], v227, s[4:5] offset:736
	global_load_dwordx4 v[126:129], v228, s[4:5] offset:736
	s_waitcnt vmcnt(45)
	v_mfma_f32_32x32x16_bf16 v[2:17], v[130:133], v[146:149], v[2:17]
	v_mfma_f32_32x32x16_bf16 v[18:33], v[130:133], v[162:165], v[18:33]
	s_waitcnt vmcnt(42)
	v_mfma_f32_32x32x16_bf16 v[2:17], v[134:137], v[150:153], v[2:17]
	v_mfma_f32_32x32x16_bf16 v[18:33], v[134:137], v[166:169], v[18:33]
	s_waitcnt vmcnt(39)
	v_mfma_f32_32x32x16_bf16 v[2:17], v[138:141], v[154:157], v[2:17]
	v_mfma_f32_32x32x16_bf16 v[18:33], v[138:141], v[170:173], v[18:33]
	s_waitcnt vmcnt(36)
	v_mfma_f32_32x32x16_bf16 v[2:17], v[142:145], v[158:161], v[2:17]
	v_mfma_f32_32x32x16_bf16 v[18:33], v[142:145], v[174:177], v[18:33]
	global_load_dwordx4 v[130:133], v226, s[20:21] offset:768
	global_load_dwordx4 v[146:149], v227, s[4:5] offset:768
	global_load_dwordx4 v[162:165], v228, s[4:5] offset:768
	global_load_dwordx4 v[134:137], v226, s[20:21] offset:800
	global_load_dwordx4 v[150:153], v227, s[4:5] offset:800
	global_load_dwordx4 v[166:169], v228, s[4:5] offset:800
	global_load_dwordx4 v[138:141], v226, s[20:21] offset:832
	global_load_dwordx4 v[154:157], v227, s[4:5] offset:832
	global_load_dwordx4 v[170:173], v228, s[4:5] offset:832
	global_load_dwordx4 v[142:145], v226, s[20:21] offset:864
	global_load_dwordx4 v[158:161], v227, s[4:5] offset:864
	global_load_dwordx4 v[174:177], v228, s[4:5] offset:864
	s_waitcnt vmcnt(45)
	v_mfma_f32_32x32x16_bf16 v[2:17], v[178:181], v[194:197], v[2:17]
	v_mfma_f32_32x32x16_bf16 v[18:33], v[178:181], v[210:213], v[18:33]
	s_waitcnt vmcnt(42)
	v_mfma_f32_32x32x16_bf16 v[2:17], v[182:185], v[198:201], v[2:17]
	v_mfma_f32_32x32x16_bf16 v[18:33], v[182:185], v[214:217], v[18:33]
	s_waitcnt vmcnt(39)
	v_mfma_f32_32x32x16_bf16 v[2:17], v[186:189], v[202:205], v[2:17]
	v_mfma_f32_32x32x16_bf16 v[18:33], v[186:189], v[218:221], v[18:33]
	s_waitcnt vmcnt(36)
	v_mfma_f32_32x32x16_bf16 v[2:17], v[190:193], v[206:209], v[2:17]
	v_mfma_f32_32x32x16_bf16 v[18:33], v[190:193], v[222:225], v[18:33]
	global_load_dwordx4 v[178:181], v226, s[20:21] offset:896
	global_load_dwordx4 v[194:197], v227, s[4:5] offset:896
	global_load_dwordx4 v[210:213], v228, s[4:5] offset:896
	global_load_dwordx4 v[182:185], v226, s[20:21] offset:928
	global_load_dwordx4 v[198:201], v227, s[4:5] offset:928
	global_load_dwordx4 v[214:217], v228, s[4:5] offset:928
	global_load_dwordx4 v[186:189], v226, s[20:21] offset:960
	global_load_dwordx4 v[202:205], v227, s[4:5] offset:960
	global_load_dwordx4 v[218:221], v228, s[4:5] offset:960
	global_load_dwordx4 v[190:193], v226, s[20:21] offset:992
	global_load_dwordx4 v[206:209], v227, s[4:5] offset:992
	global_load_dwordx4 v[222:225], v228, s[4:5] offset:992
	s_waitcnt vmcnt(45)
	v_mfma_f32_32x32x16_bf16 v[2:17], v[34:37], v[50:53], v[2:17]
	v_mfma_f32_32x32x16_bf16 v[18:33], v[34:37], v[66:69], v[18:33]
	s_waitcnt vmcnt(42)
	v_mfma_f32_32x32x16_bf16 v[2:17], v[38:41], v[54:57], v[2:17]
	v_mfma_f32_32x32x16_bf16 v[18:33], v[38:41], v[70:73], v[18:33]
	s_waitcnt vmcnt(39)
	v_mfma_f32_32x32x16_bf16 v[2:17], v[42:45], v[58:61], v[2:17]
	v_mfma_f32_32x32x16_bf16 v[18:33], v[42:45], v[74:77], v[18:33]
	s_waitcnt vmcnt(36)
	v_mfma_f32_32x32x16_bf16 v[2:17], v[46:49], v[62:65], v[2:17]
	v_mfma_f32_32x32x16_bf16 v[18:33], v[46:49], v[78:81], v[18:33]
	s_waitcnt vmcnt(33)
	v_mfma_f32_32x32x16_bf16 v[2:17], v[82:85], v[98:101], v[2:17]
	v_mfma_f32_32x32x16_bf16 v[18:33], v[82:85], v[114:117], v[18:33]
	s_waitcnt vmcnt(30)
	v_mfma_f32_32x32x16_bf16 v[2:17], v[86:89], v[102:105], v[2:17]
	v_mfma_f32_32x32x16_bf16 v[18:33], v[86:89], v[118:121], v[18:33]
	s_waitcnt vmcnt(27)
	v_mfma_f32_32x32x16_bf16 v[2:17], v[90:93], v[106:109], v[2:17]
	v_mfma_f32_32x32x16_bf16 v[18:33], v[90:93], v[122:125], v[18:33]
	s_waitcnt vmcnt(24)
	v_mfma_f32_32x32x16_bf16 v[2:17], v[94:97], v[110:113], v[2:17]
	v_mfma_f32_32x32x16_bf16 v[18:33], v[94:97], v[126:129], v[18:33]
	s_waitcnt vmcnt(21)
	v_mfma_f32_32x32x16_bf16 v[2:17], v[130:133], v[146:149], v[2:17]
	v_mfma_f32_32x32x16_bf16 v[18:33], v[130:133], v[162:165], v[18:33]
	s_waitcnt vmcnt(18)
	v_mfma_f32_32x32x16_bf16 v[2:17], v[134:137], v[150:153], v[2:17]
	v_mfma_f32_32x32x16_bf16 v[18:33], v[134:137], v[166:169], v[18:33]
	s_waitcnt vmcnt(15)
	v_mfma_f32_32x32x16_bf16 v[2:17], v[138:141], v[154:157], v[2:17]
	v_mfma_f32_32x32x16_bf16 v[18:33], v[138:141], v[170:173], v[18:33]
	s_waitcnt vmcnt(12)
	v_mfma_f32_32x32x16_bf16 v[2:17], v[142:145], v[158:161], v[2:17]
	v_mfma_f32_32x32x16_bf16 v[18:33], v[142:145], v[174:177], v[18:33]
	s_waitcnt vmcnt(9)
	v_mfma_f32_32x32x16_bf16 v[2:17], v[178:181], v[194:197], v[2:17]
	v_mfma_f32_32x32x16_bf16 v[18:33], v[178:181], v[210:213], v[18:33]
	s_waitcnt vmcnt(6)
	v_mfma_f32_32x32x16_bf16 v[2:17], v[182:185], v[198:201], v[2:17]
	v_mfma_f32_32x32x16_bf16 v[18:33], v[182:185], v[214:217], v[18:33]
	s_waitcnt vmcnt(3)
	v_mfma_f32_32x32x16_bf16 v[2:17], v[186:189], v[202:205], v[2:17]
	v_mfma_f32_32x32x16_bf16 v[18:33], v[186:189], v[218:221], v[18:33]
	s_waitcnt vmcnt(0)
	v_mfma_f32_32x32x16_bf16 v[2:17], v[190:193], v[206:209], v[2:17]
	v_mfma_f32_32x32x16_bf16 v[18:33], v[190:193], v[222:225], v[18:33]
	s_nop 15
	s_nop 3
	global_store_dword v229, v2, s[22:23]
	global_store_dword v229, v18, s[22:23] offset:128
	v_add_u32_e32 v231, 0x1000, v229
	global_store_dword v231, v3, s[22:23]
	global_store_dword v231, v19, s[22:23] offset:128
	v_add_u32_e32 v230, 0x2000, v229
	global_store_dword v230, v4, s[22:23]
	global_store_dword v230, v20, s[22:23] offset:128
	v_add_u32_e32 v231, 0x3000, v229
	global_store_dword v231, v5, s[22:23]
	global_store_dword v231, v21, s[22:23] offset:128
	v_add_u32_e32 v230, 0x8000, v229
	global_store_dword v230, v6, s[22:23]
	global_store_dword v230, v22, s[22:23] offset:128
	v_add_u32_e32 v231, 0x9000, v229
	global_store_dword v231, v7, s[22:23]
	global_store_dword v231, v23, s[22:23] offset:128
	v_add_u32_e32 v230, 0xa000, v229
	global_store_dword v230, v8, s[22:23]
	global_store_dword v230, v24, s[22:23] offset:128
	v_add_u32_e32 v231, 0xb000, v229
	global_store_dword v231, v9, s[22:23]
	global_store_dword v231, v25, s[22:23] offset:128
	v_add_u32_e32 v230, 0x10000, v229
	global_store_dword v230, v10, s[22:23]
	global_store_dword v230, v26, s[22:23] offset:128
	v_add_u32_e32 v231, 0x11000, v229
	global_store_dword v231, v11, s[22:23]
	global_store_dword v231, v27, s[22:23] offset:128
	v_add_u32_e32 v230, 0x12000, v229
	global_store_dword v230, v12, s[22:23]
	global_store_dword v230, v28, s[22:23] offset:128
	v_add_u32_e32 v231, 0x13000, v229
	global_store_dword v231, v13, s[22:23]
	global_store_dword v231, v29, s[22:23] offset:128
	v_add_u32_e32 v230, 0x18000, v229
	global_store_dword v230, v14, s[22:23]
	global_store_dword v230, v30, s[22:23] offset:128
	v_add_u32_e32 v231, 0x19000, v229
	global_store_dword v231, v15, s[22:23]
	global_store_dword v231, v31, s[22:23] offset:128
	v_add_u32_e32 v230, 0x1a000, v229
	global_store_dword v230, v16, s[22:23]
	global_store_dword v230, v32, s[22:23] offset:128
	v_add_u32_e32 v231, 0x1b000, v229
	global_store_dword v231, v17, s[22:23]
	global_store_dword v231, v33, s[22:23] offset:128
	s_add_i32 s12, s12, s24
	s_cmpk_lt_i32 s12, 0x200
	s_cbranch_scc1 .Lsg10_unit

	.amdhsa_kernel _Z10fwd_kernelILi10ELi11EEv4Args
		.amdhsa_group_segment_fixed_size 0
		.amdhsa_private_segment_fixed_size 0
		.amdhsa_kernarg_size 488
		.amdhsa_user_sgpr_count 2
		.amdhsa_user_sgpr_dispatch_ptr 0
		.amdhsa_user_sgpr_queue_ptr 0
		.amdhsa_user_sgpr_kernarg_segment_ptr 1
		.amdhsa_user_sgpr_dispatch_id 0
		.amdhsa_user_sgpr_kernarg_preload_length 0
		.amdhsa_user_sgpr_kernarg_preload_offset 0
		.amdhsa_user_sgpr_private_segment_size 0
		.amdhsa_uses_dynamic_stack 0
		.amdhsa_enable_private_segment 0
		.amdhsa_system_sgpr_workgroup_id_x 1
		.amdhsa_system_sgpr_workgroup_id_y 0
		.amdhsa_system_sgpr_workgroup_id_z 0
		.amdhsa_system_sgpr_workgroup_info 0
		.amdhsa_system_vgpr_workitem_id 0
		.amdhsa_next_free_vgpr 240
		.amdhsa_next_free_sgpr 61
		.amdhsa_accum_offset 240
		.amdhsa_reserve_vcc 1
		.amdhsa_float_round_mode_32 0
		.amdhsa_float_round_mode_16_64 0
		.amdhsa_float_denorm_mode_32 3
		.amdhsa_float_denorm_mode_16_64 3
		.amdhsa_dx10_clamp 1
		.amdhsa_ieee_mode 1
		.amdhsa_fp16_overflow 0
		.amdhsa_tg_split 0
		.amdhsa_exception_fp_ieee_invalid_op 0
		.amdhsa_exception_fp_denorm_src 0
		.amdhsa_exception_fp_ieee_div_zero 0
		.amdhsa_exception_fp_ieee_overflow 0
		.amdhsa_exception_fp_ieee_underflow 0
		.amdhsa_exception_fp_ieee_inexact 0
		.amdhsa_exception_int_div_zero 0
	.end_amdhsa_kernel

_Z10fwd_kernelILi13ELi14EEv4Args:
	v_mov_b32_e32 v1, v0
	s_load_dword s3, s[0:1], 0xe8
	s_load_dwordx2 s[0:1], s[0:1], 0xd8
	v_readfirstlane_b32 s4, v1
	s_ashr_i32 s6, s4, 6
	s_waitcnt lgkmcnt(0)
	s_add_u32 s4, s0, 0x2900000
	s_addc_u32 s5, s1, 0
	s_lshl_b32 s7, s2, 3
	s_add_i32 s14, s7, s6
	s_cmpk_gt_i32 s14, 0x7ff
	s_cbranch_scc1 .LBB13_3
	s_add_u32 s20, s0, 0xf400000
	s_addc_u32 s21, s1, 0
	s_add_u32 s22, s0, 0x100000
	s_addc_u32 s23, s1, 0
	s_lshl_b32 s24, s3, 3
	v_and_b32_e32 v234, 31, v0
	v_bfe_u32 v235, v0, 5, 1
	v_lshlrev_b32_e32 v232, 13, v234
	v_lshl_add_u32 v232, v235, 4, v232
	v_lshlrev_b32_e32 v233, 2, v234
	v_lshl_add_u32 v233, v235, 14, v233
.Lsg13_unit:
	s_and_b32 s28, s14, 7
	s_lshr_b32 s29, s14, 3
	s_bfe_u32 s25, s29, 0x30001
	s_lshr_b32 s26, s29, 4
	s_and_b32 s27, s29, 1
	s_lshl_b32 s27, s27, 3
	s_add_u32 s27, s27, s28
	s_lshl_b32 s30, s25, 10
	s_lshl_b32 s31, s27, 18
	s_add_u32 s31, s31, s30
	s_lshl_b32 s33, s26, 19
	s_add_u32 s33, s33, s30
	v_add_u32_e32 v226, s31, v232
	v_add_u32_e32 v227, s33, v232
	v_add_u32_e32 v228, 0x40000, v227
	s_lshl_b32 s34, s25, 21
	s_lshl_b32 s35, s27, 17
	s_add_u32 s34, s34, s35
	s_lshl_b32 s35, s26, 8
	s_add_u32 s34, s34, s35
	v_add_u32_e32 v229, s34, v233
	global_load_dwordx4 v[34:37], v226, s[20:21] offset:0
	global_load_dwordx4 v[50:53], v227, s[4:5] offset:0
	global_load_dwordx4 v[66:69], v228, s[4:5] offset:0
	global_load_dwordx4 v[38:41], v226, s[20:21] offset:32
	global_load_dwordx4 v[54:57], v227, s[4:5] offset:32
	global_load_dwordx4 v[70:73], v228, s[4:5] offset:32
	global_load_dwordx4 v[42:45], v226, s[20:21] offset:64
	global_load_dwordx4 v[58:61], v227, s[4:5] offset:64
	global_load_dwordx4 v[74:77], v228, s[4:5] offset:64
	global_load_dwordx4 v[46:49], v226, s[20:21] offset:96
	global_load_dwordx4 v[62:65], v227, s[4:5] offset:96
	global_load_dwordx4 v[78:81], v228, s[4:5] offset:96
	global_load_dwordx4 v[82:85], v226, s[20:21] offset:128
	global_load_dwordx4 v[98:101], v227, s[4:5] offset:128
	global_load_dwordx4 v[114:117], v228, s[4:5] offset:128
	global_load_dwordx4 v[86:89], v226, s[20:21] offset:160
	global_load_dwordx4 v[102:105], v227, s[4:5] offset:160
	global_load_dwordx4 v[118:121], v228, s[4:5] offset:160
	global_load_dwordx4 v[90:93], v226, s[20:21] offset:192
	global_load_dwordx4 v[106:109], v227, s[4:5] offset:192
	global_load_dwordx4 v[122:125], v228, s[4:5] offset:192
	global_load_dwordx4 v[94:97], v226, s[20:21] offset:224
	global_load_dwordx4 v[110:113], v227, s[4:5] offset:224
	global_load_dwordx4 v[126:129], v228, s[4:5] offset:224
	global_load_dwordx4 v[130:133], v226, s[20:21] offset:256
	global_load_dwordx4 v[146:149], v227, s[4:5] offset:256
	global_load_dwordx4 v[162:165], v228, s[4:5] offset:256
	global_load_dwordx4 v[134:137], v226, s[20:21] offset:288
	global_load_dwordx4 v[150:153], v227, s[4:5] offset:288
	global_load_dwordx4 v[166:169], v228, s[4:5] offset:288
	global_load_dwordx4 v[138:141], v226, s[20:21] offset:320
	global_load_dwordx4 v[154:157], v227, s[4:5] offset:320
	global_load_dwordx4 v[170:173], v228, s[4:5] offset:320
	global_load_dwordx4 v[142:145], v226, s[20:21] offset:352
	global_load_dwordx4 v[158:161], v227, s[4:5] offset:352
	global_load_dwordx4 v[174:177], v228, s[4:5] offset:352
	global_load_dwordx4 v[178:181], v226, s[20:21] offset:384
	global_load_dwordx4 v[194:197], v227, s[4:5] offset:384
	global_load_dwordx4 v[210:213], v228, s[4:5] offset:384
	global_load_dwordx4 v[182:185], v226, s[20:21] offset:416
	global_load_dwordx4 v[198:201], v227, s[4:5] offset:416
	global_load_dwordx4 v[214:217], v228, s[4:5] offset:416
	global_load_dwordx4 v[186:189], v226, s[20:21] offset:448
	global_load_dwordx4 v[202:205], v227, s[4:5] offset:448
	global_load_dwordx4 v[218:221], v228, s[4:5] offset:448
	global_load_dwordx4 v[190:193], v226, s[20:21] offset:480
	global_load_dwordx4 v[206:209], v227, s[4:5] offset:480
	global_load_dwordx4 v[222:225], v228, s[4:5] offset:480
	s_waitcnt vmcnt(45)
	v_mfma_f32_32x32x16_bf16 v[2:17], v[34:37], v[50:53], 0
	v_mfma_f32_32x32x16_bf16 v[18:33], v[34:37], v[66:69], 0
	s_waitcnt vmcnt(42)
	v_mfma_f32_32x32x16_bf16 v[2:17], v[38:41], v[54:57], v[2:17]
	v_mfma_f32_32x32x16_bf16 v[18:33], v[38:41], v[70:73], v[18:33]
	s_waitcnt vmcnt(39)
	v_mfma_f32_32x32x16_bf16 v[2:17], v[42:45], v[58:61], v[2:17]
	v_mfma_f32_32x32x16_bf16 v[18:33], v[42:45], v[74:77], v[18:33]
	s_waitcnt vmcnt(36)
	v_mfma_f32_32x32x16_bf16 v[2:17], v[46:49], v[62:65], v[2:17]
	v_mfma_f32_32x32x16_bf16 v[18:33], v[46:49], v[78:81], v[18:33]
	global_load_dwordx4 v[34:37], v226, s[20:21] offset:512
	global_load_dwordx4 v[50:53], v227, s[4:5] offset:512
	global_load_dwordx4 v[66:69], v228, s[4:5] offset:512
	global_load_dwordx4 v[38:41], v226, s[20:21] offset:544
	global_load_dwordx4 v[54:57], v227, s[4:5] offset:544
	global_load_dwordx4 v[70:73], v228, s[4:5] offset:544
	global_load_dwordx4 v[42:45], v226, s[20:21] offset:576
	global_load_dwordx4 v[58:61], v227, s[4:5] offset:576
	global_load_dwordx4 v[74:77], v228, s[4:5] offset:576
	global_load_dwordx4 v[46:49], v226, s[20:21] offset:608
	global_load_dwordx4 v[62:65], v227, s[4:5] offset:608
	global_load_dwordx4 v[78:81], v228, s[4:5] offset:608
	s_waitcnt vmcnt(45)
	v_mfma_f32_32x32x16_bf16 v[2:17], v[82:85], v[98:101], v[2:17]
	v_mfma_f32_32x32x16_bf16 v[18:33], v[82:85], v[114:117], v[18:33]
	s_waitcnt vmcnt(42)
	v_mfma_f32_32x32x16_bf16 v[2:17], v[86:89], v[102:105], v[2:17]
	v_mfma_f32_32x32x16_bf16 v[18:33], v[86:89], v[118:121], v[18:33]
	s_waitcnt vmcnt(39)
	v_mfma_f32_32x32x16_bf16 v[2:17], v[90:93], v[106:109], v[2:17]
	v_mfma_f32_32x32x16_bf16 v[18:33], v[90:93], v[122:125], v[18:33]
	s_waitcnt vmcnt(36)
	v_mfma_f32_32x32x16_bf16 v[2:17], v[94:97], v[110:113], v[2:17]
	v_mfma_f32_32x32x16_bf16 v[18:33], v[94:97], v[126:129], v[18:33]
	global_load_dwordx4 v[82:85], v226, s[20:21] offset:640
	global_load_dwordx4 v[98:101], v227, s[4:5] offset:640
	global_load_dwordx4 v[114:117], v228, s[4:5] offset:640
	global_load_dwordx4 v[86:89], v226, s[20:21] offset:672
	global_load_dwordx4 v[102:105], v227, s[4:5] offset:672
	global_load_dwordx4 v[118:121], v228, s[4:5] offset:672
	global_load_dwordx4 v[90:93], v226, s[20:21] offset:704
	global_load_dwordx4 v[106:109], v227, s[4:5] offset:704
	global_load_dwordx4 v[122:125], v228, s[4:5] offset:704
	global_load_dwordx4 v[94:97], v226, s[20:21] offset:736
	global_load_dwordx4 v[110:113], v227, s[4:5] offset:736
	global_load_dwordx4 v[126:129], v228, s[4:5] offset:736
	s_waitcnt vmcnt(45)
	v_mfma_f32_32x32x16_bf16 v[2:17], v[130:133], v[146:149], v[2:17]
	v_mfma_f32_32x32x16_bf16 v[18:33], v[130:133], v[162:165], v[18:33]
	s_waitcnt vmcnt(42)
	v_mfma_f32_32x32x16_bf16 v[2:17], v[134:137], v[150:153], v[2:17]
	v_mfma_f32_32x32x16_bf16 v[18:33], v[134:137], v[166:169], v[18:33]
	s_waitcnt vmcnt(39)
	v_mfma_f32_32x32x16_bf16 v[2:17], v[138:141], v[154:157], v[2:17]
	v_mfma_f32_32x32x16_bf16 v[18:33], v[138:141], v[170:173], v[18:33]
	s_waitcnt vmcnt(36)
	v_mfma_f32_32x32x16_bf16 v[2:17], v[142:145], v[158:161], v[2:17]
	v_mfma_f32_32x32x16_bf16 v[18:33], v[142:145], v[174:177], v[18:33]
	global_load_dwordx4 v[130:133], v226, s[20:21] offset:768
	global_load_dwordx4 v[146:149], v227, s[4:5] offset:768
	global_load_dwordx4 v[162:165], v228, s[4:5] offset:768
	global_load_dwordx4 v[134:137], v226, s[20:21] offset:800
	global_load_dwordx4 v[150:153], v227, s[4:5] offset:800
	global_load_dwordx4 v[166:169], v228, s[4:5] offset:800
	global_load_dwordx4 v[138:141], v226, s[20:21] offset:832
	global_load_dwordx4 v[154:157], v227, s[4:5] offset:832
	global_load_dwordx4 v[170:173], v228, s[4:5] offset:832
	global_load_dwordx4 v[142:145], v226, s[20:21] offset:864
	global_load_dwordx4 v[158:161], v227, s[4:5] offset:864
	global_load_dwordx4 v[174:177], v228, s[4:5] offset:864
	s_waitcnt vmcnt(45)
	v_mfma_f32_32x32x16_bf16 v[2:17], v[178:181], v[194:197], v[2:17]
	v_mfma_f32_32x32x16_bf16 v[18:33], v[178:181], v[210:213], v[18:33]
	s_waitcnt vmcnt(42)
	v_mfma_f32_32x32x16_bf16 v[2:17], v[182:185], v[198:201], v[2:17]
	v_mfma_f32_32x32x16_bf16 v[18:33], v[182:185], v[214:217], v[18:33]
	s_waitcnt vmcnt(39)
	v_mfma_f32_32x32x16_bf16 v[2:17], v[186:189], v[202:205], v[2:17]
	v_mfma_f32_32x32x16_bf16 v[18:33], v[186:189], v[218:221], v[18:33]
	s_waitcnt vmcnt(36)
	v_mfma_f32_32x32x16_bf16 v[2:17], v[190:193], v[206:209], v[2:17]
	v_mfma_f32_32x32x16_bf16 v[18:33], v[190:193], v[222:225], v[18:33]
	global_load_dwordx4 v[178:181], v226, s[20:21] offset:896
	global_load_dwordx4 v[194:197], v227, s[4:5] offset:896
	global_load_dwordx4 v[210:213], v228, s[4:5] offset:896
	global_load_dwordx4 v[182:185], v226, s[20:21] offset:928
	global_load_dwordx4 v[198:201], v227, s[4:5] offset:928
	global_load_dwordx4 v[214:217], v228, s[4:5] offset:928
	global_load_dwordx4 v[186:189], v226, s[20:21] offset:960
	global_load_dwordx4 v[202:205], v227, s[4:5] offset:960
	global_load_dwordx4 v[218:221], v228, s[4:5] offset:960
	global_load_dwordx4 v[190:193], v226, s[20:21] offset:992
	global_load_dwordx4 v[206:209], v227, s[4:5] offset:992
	global_load_dwordx4 v[222:225], v228, s[4:5] offset:992
	s_waitcnt vmcnt(45)
	v_mfma_f32_32x32x16_bf16 v[2:17], v[34:37], v[50:53], v[2:17]
	v_mfma_f32_32x32x16_bf16 v[18:33], v[34:37], v[66:69], v[18:33]
	s_waitcnt vmcnt(42)
	v_mfma_f32_32x32x16_bf16 v[2:17], v[38:41], v[54:57], v[2:17]
	v_mfma_f32_32x32x16_bf16 v[18:33], v[38:41], v[70:73], v[18:33]
	s_waitcnt vmcnt(39)
	v_mfma_f32_32x32x16_bf16 v[2:17], v[42:45], v[58:61], v[2:17]
	v_mfma_f32_32x32x16_bf16 v[18:33], v[42:45], v[74:77], v[18:33]
	s_waitcnt vmcnt(36)
	v_mfma_f32_32x32x16_bf16 v[2:17], v[46:49], v[62:65], v[2:17]
	v_mfma_f32_32x32x16_bf16 v[18:33], v[46:49], v[78:81], v[18:33]
	s_waitcnt vmcnt(33)
	v_mfma_f32_32x32x16_bf16 v[2:17], v[82:85], v[98:101], v[2:17]
	v_mfma_f32_32x32x16_bf16 v[18:33], v[82:85], v[114:117], v[18:33]
	s_waitcnt vmcnt(30)
	v_mfma_f32_32x32x16_bf16 v[2:17], v[86:89], v[102:105], v[2:17]
	v_mfma_f32_32x32x16_bf16 v[18:33], v[86:89], v[118:121], v[18:33]
	s_waitcnt vmcnt(27)
	v_mfma_f32_32x32x16_bf16 v[2:17], v[90:93], v[106:109], v[2:17]
	v_mfma_f32_32x32x16_bf16 v[18:33], v[90:93], v[122:125], v[18:33]
	s_waitcnt vmcnt(24)
	v_mfma_f32_32x32x16_bf16 v[2:17], v[94:97], v[110:113], v[2:17]
	v_mfma_f32_32x32x16_bf16 v[18:33], v[94:97], v[126:129], v[18:33]
	s_waitcnt vmcnt(21)
	v_mfma_f32_32x32x16_bf16 v[2:17], v[130:133], v[146:149], v[2:17]
	v_mfma_f32_32x32x16_bf16 v[18:33], v[130:133], v[162:165], v[18:33]
	s_waitcnt vmcnt(18)
	v_mfma_f32_32x32x16_bf16 v[2:17], v[134:137], v[150:153], v[2:17]
	v_mfma_f32_32x32x16_bf16 v[18:33], v[134:137], v[166:169], v[18:33]
	s_waitcnt vmcnt(15)
	v_mfma_f32_32x32x16_bf16 v[2:17], v[138:141], v[154:157], v[2:17]
	v_mfma_f32_32x32x16_bf16 v[18:33], v[138:141], v[170:173], v[18:33]
	s_waitcnt vmcnt(12)
	v_mfma_f32_32x32x16_bf16 v[2:17], v[142:145], v[158:161], v[2:17]
	v_mfma_f32_32x32x16_bf16 v[18:33], v[142:145], v[174:177], v[18:33]
	s_waitcnt vmcnt(9)
	v_mfma_f32_32x32x16_bf16 v[2:17], v[178:181], v[194:197], v[2:17]
	v_mfma_f32_32x32x16_bf16 v[18:33], v[178:181], v[210:213], v[18:33]
	s_waitcnt vmcnt(6)
	v_mfma_f32_32x32x16_bf16 v[2:17], v[182:185], v[198:201], v[2:17]
	v_mfma_f32_32x32x16_bf16 v[18:33], v[182:185], v[214:217], v[18:33]
	s_waitcnt vmcnt(3)
	v_mfma_f32_32x32x16_bf16 v[2:17], v[186:189], v[202:205], v[2:17]
	v_mfma_f32_32x32x16_bf16 v[18:33], v[186:189], v[218:221], v[18:33]
	s_waitcnt vmcnt(0)
	v_mfma_f32_32x32x16_bf16 v[2:17], v[190:193], v[206:209], v[2:17]
	v_mfma_f32_32x32x16_bf16 v[18:33], v[190:193], v[222:225], v[18:33]
	s_nop 15
	s_nop 3
	global_store_dword v229, v2, s[22:23]
	global_store_dword v229, v18, s[22:23] offset:128
	v_add_u32_e32 v231, 0x1000, v229
	global_store_dword v231, v3, s[22:23]
	global_store_dword v231, v19, s[22:23] offset:128
	v_add_u32_e32 v230, 0x2000, v229
	global_store_dword v230, v4, s[22:23]
	global_store_dword v230, v20, s[22:23] offset:128
	v_add_u32_e32 v231, 0x3000, v229
	global_store_dword v231, v5, s[22:23]
	global_store_dword v231, v21, s[22:23] offset:128
	v_add_u32_e32 v230, 0x8000, v229
	global_store_dword v230, v6, s[22:23]
	global_store_dword v230, v22, s[22:23] offset:128
	v_add_u32_e32 v231, 0x9000, v229
	global_store_dword v231, v7, s[22:23]
	global_store_dword v231, v23, s[22:23] offset:128
	v_add_u32_e32 v230, 0xa000, v229
	global_store_dword v230, v8, s[22:23]
	global_store_dword v230, v24, s[22:23] offset:128
	v_add_u32_e32 v231, 0xb000, v229
	global_store_dword v231, v9, s[22:23]
	global_store_dword v231, v25, s[22:23] offset:128
	v_add_u32_e32 v230, 0x10000, v229
	global_store_dword v230, v10, s[22:23]
	global_store_dword v230, v26, s[22:23] offset:128
	v_add_u32_e32 v231, 0x11000, v229
	global_store_dword v231, v11, s[22:23]
	global_store_dword v231, v27, s[22:23] offset:128
	v_add_u32_e32 v230, 0x12000, v229
	global_store_dword v230, v12, s[22:23]
	global_store_dword v230, v28, s[22:23] offset:128
	v_add_u32_e32 v231, 0x13000, v229
	global_store_dword v231, v13, s[22:23]
	global_store_dword v231, v29, s[22:23] offset:128
	v_add_u32_e32 v230, 0x18000, v229
	global_store_dword v230, v14, s[22:23]
	global_store_dword v230, v30, s[22:23] offset:128
	v_add_u32_e32 v231, 0x19000, v229
	global_store_dword v231, v15, s[22:23]
	global_store_dword v231, v31, s[22:23] offset:128
	v_add_u32_e32 v230, 0x1a000, v229
	global_store_dword v230, v16, s[22:23]
	global_store_dword v230, v32, s[22:23] offset:128
	v_add_u32_e32 v231, 0x1b000, v229
	global_store_dword v231, v17, s[22:23]
	global_store_dword v231, v33, s[22:23] offset:128
	s_add_i32 s14, s14, s24
	s_cmpk_lt_i32 s14, 0x800
	s_cbranch_scc1 .Lsg13_unit

	.amdhsa_kernel _Z10fwd_kernelILi13ELi14EEv4Args
		.amdhsa_group_segment_fixed_size 0
		.amdhsa_private_segment_fixed_size 0
		.amdhsa_kernarg_size 488
		.amdhsa_user_sgpr_count 2
		.amdhsa_user_sgpr_dispatch_ptr 0
		.amdhsa_user_sgpr_queue_ptr 0
		.amdhsa_user_sgpr_kernarg_segment_ptr 1
		.amdhsa_user_sgpr_dispatch_id 0
		.amdhsa_user_sgpr_kernarg_preload_length 0
		.amdhsa_user_sgpr_kernarg_preload_offset 0
		.amdhsa_user_sgpr_private_segment_size 0
		.amdhsa_uses_dynamic_stack 0
		.amdhsa_enable_private_segment 0
		.amdhsa_system_sgpr_workgroup_id_x 1
		.amdhsa_system_sgpr_workgroup_id_y 0
		.amdhsa_system_sgpr_workgroup_id_z 0
		.amdhsa_system_sgpr_workgroup_info 0
		.amdhsa_system_vgpr_workitem_id 0
		.amdhsa_next_free_vgpr 240
		.amdhsa_next_free_sgpr 61
		.amdhsa_accum_offset 240
		.amdhsa_reserve_vcc 1
		.amdhsa_float_round_mode_32 0
		.amdhsa_float_round_mode_16_64 0
		.amdhsa_float_denorm_mode_32 3
		.amdhsa_float_denorm_mode_16_64 3
		.amdhsa_dx10_clamp 1
		.amdhsa_ieee_mode 1
		.amdhsa_fp16_overflow 0
		.amdhsa_tg_split 0
		.amdhsa_exception_fp_ieee_invalid_op 0
		.amdhsa_exception_fp_denorm_src 0
		.amdhsa_exception_fp_ieee_div_zero 0
		.amdhsa_exception_fp_ieee_overflow 0
		.amdhsa_exception_fp_ieee_underflow 0
		.amdhsa_exception_fp_ieee_inexact 0
		.amdhsa_exception_int_div_zero 0
	.end_amdhsa_kernel

amdhsa.kernels:
  - .agpr_count:     0
    .args:
      - .offset:         0
        .size:           232
        .value_kind:     by_value
      - .offset:         232
        .size:           4
        .value_kind:     hidden_block_count_x
      - .offset:         236
        .size:           4
        .value_kind:     hidden_block_count_y
      - .offset:         240
        .size:           4
        .value_kind:     hidden_block_count_z
      - .offset:         244
        .size:           2
        .value_kind:     hidden_group_size_x
      - .offset:         246
        .size:           2
        .value_kind:     hidden_group_size_y
      - .offset:         248
        .size:           2
        .value_kind:     hidden_group_size_z
      - .offset:         250
        .size:           2
        .value_kind:     hidden_remainder_x
      - .offset:         252
        .size:           2
        .value_kind:     hidden_remainder_y
      - .offset:         254
        .size:           2
        .value_kind:     hidden_remainder_z
      - .offset:         272
        .size:           8
        .value_kind:     hidden_global_offset_x
      - .offset:         280
        .size:           8
        .value_kind:     hidden_global_offset_y
      - .offset:         288
        .size:           8
        .value_kind:     hidden_global_offset_z
      - .offset:         296
        .size:           2
        .value_kind:     hidden_grid_dims
      - .offset:         352
        .size:           4
        .value_kind:     hidden_dynamic_lds_size
    .group_segment_fixed_size: 0
    .kernarg_segment_align: 8
    .kernarg_segment_size: 488
    .language:       OpenCL C
    .language_version:
      - 2
      - 0
    .max_flat_workgroup_size: 512
    .name:           _Z10fwd_kernelILi0ELi1EEv4Args
    .private_segment_fixed_size: 0
    .sgpr_count:     106
    .sgpr_spill_count: 0
    .symbol:         _Z10fwd_kernelILi0ELi1EEv4Args.kd
    .uniform_work_group_size: 1
    .uses_dynamic_stack: false
    .vgpr_count:     224
    .vgpr_spill_count: 0
    .wavefront_size: 64
  - .agpr_count:     0
    .args:
      - .offset:         0
        .size:           232
        .value_kind:     by_value
      - .offset:         232
        .size:           4
        .value_kind:     hidden_block_count_x
      - .offset:         236
        .size:           4
        .value_kind:     hidden_block_count_y
      - .offset:         240
        .size:           4
        .value_kind:     hidden_block_count_z
      - .offset:         244
        .size:           2
        .value_kind:     hidden_group_size_x
      - .offset:         246
        .size:           2
        .value_kind:     hidden_group_size_y
      - .offset:         248
        .size:           2
        .value_kind:     hidden_group_size_z
      - .offset:         250
        .size:           2
        .value_kind:     hidden_remainder_x
      - .offset:         252
        .size:           2
        .value_kind:     hidden_remainder_y
      - .offset:         254
        .size:           2
        .value_kind:     hidden_remainder_z
      - .offset:         272
        .size:           8
        .value_kind:     hidden_global_offset_x
      - .offset:         280
        .size:           8
        .value_kind:     hidden_global_offset_y
      - .offset:         288
        .size:           8
        .value_kind:     hidden_global_offset_z
      - .offset:         296
        .size:           2
        .value_kind:     hidden_grid_dims
      - .offset:         352
        .size:           4
        .value_kind:     hidden_dynamic_lds_size
    .group_segment_fixed_size: 0
    .kernarg_segment_align: 8
    .kernarg_segment_size: 488
    .language:       OpenCL C
    .language_version:
      - 2
      - 0
    .max_flat_workgroup_size: 512
    .name:           _Z10fwd_kernelILi1ELi2EEv4Args
    .private_segment_fixed_size: 0
    .sgpr_count:     64
    .sgpr_spill_count: 0
    .symbol:         _Z10fwd_kernelILi1ELi2EEv4Args.kd
    .uniform_work_group_size: 1
    .uses_dynamic_stack: false
    .vgpr_count:     226
    .vgpr_spill_count: 0
    .wavefront_size: 64
  - .agpr_count:     0
    .args:
      - .offset:         0
        .size:           232
        .value_kind:     by_value
      - .offset:         232
        .size:           4
        .value_kind:     hidden_block_count_x
      - .offset:         236
        .size:           4
        .value_kind:     hidden_block_count_y
      - .offset:         240
        .size:           4
        .value_kind:     hidden_block_count_z
      - .offset:         244
        .size:           2
        .value_kind:     hidden_group_size_x
      - .offset:         246
        .size:           2
        .value_kind:     hidden_group_size_y
      - .offset:         248
        .size:           2
        .value_kind:     hidden_group_size_z
      - .offset:         250
        .size:           2
        .value_kind:     hidden_remainder_x
      - .offset:         252
        .size:           2
        .value_kind:     hidden_remainder_y
      - .offset:         254
        .size:           2
        .value_kind:     hidden_remainder_z
      - .offset:         272
        .size:           8
        .value_kind:     hidden_global_offset_x
      - .offset:         280
        .size:           8
        .value_kind:     hidden_global_offset_y
      - .offset:         288
        .size:           8
        .value_kind:     hidden_global_offset_z
      - .offset:         296
        .size:           2
        .value_kind:     hidden_grid_dims
      - .offset:         352
        .size:           4
        .value_kind:     hidden_dynamic_lds_size
    .group_segment_fixed_size: 0
    .kernarg_segment_align: 8
    .kernarg_segment_size: 488
    .language:       OpenCL C
    .language_version:
      - 2
      - 0
    .max_flat_workgroup_size: 512
    .name:           _Z10fwd_kernelILi2ELi3EEv4Args
    .private_segment_fixed_size: 0
    .sgpr_count:     106
    .sgpr_spill_count: 11
    .symbol:         _Z10fwd_kernelILi2ELi3EEv4Args.kd
    .uniform_work_group_size: 1
    .uses_dynamic_stack: false
    .vgpr_count:     252
    .vgpr_spill_count: 0
    .wavefront_size: 64
  - .agpr_count:     0
    .args:
      - .offset:         0
        .size:           232
        .value_kind:     by_value
      - .offset:         232
        .size:           4
        .value_kind:     hidden_block_count_x
      - .offset:         236
        .size:           4
        .value_kind:     hidden_block_count_y
      - .offset:         240
        .size:           4
        .value_kind:     hidden_block_count_z
      - .offset:         244
        .size:           2
        .value_kind:     hidden_group_size_x
      - .offset:         246
        .size:           2
        .value_kind:     hidden_group_size_y
      - .offset:         248
        .size:           2
        .value_kind:     hidden_group_size_z
      - .offset:         250
        .size:           2
        .value_kind:     hidden_remainder_x
      - .offset:         252
        .size:           2
        .value_kind:     hidden_remainder_y
      - .offset:         254
        .size:           2
        .value_kind:     hidden_remainder_z
      - .offset:         272
        .size:           8
        .value_kind:     hidden_global_offset_x
      - .offset:         280
        .size:           8
        .value_kind:     hidden_global_offset_y
      - .offset:         288
        .size:           8
        .value_kind:     hidden_global_offset_z
      - .offset:         296
        .size:           2
        .value_kind:     hidden_grid_dims
      - .offset:         352
        .size:           4
        .value_kind:     hidden_dynamic_lds_size
    .group_segment_fixed_size: 0
    .kernarg_segment_align: 8
    .kernarg_segment_size: 488
    .language:       OpenCL C
    .language_version:
      - 2
      - 0
    .max_flat_workgroup_size: 512
    .name:           _Z10fwd_kernelILi3ELi4EEv4Args
    .private_segment_fixed_size: 0
    .sgpr_count:     67
    .sgpr_spill_count: 0
    .symbol:         _Z10fwd_kernelILi3ELi4EEv4Args.kd
    .uniform_work_group_size: 1
    .uses_dynamic_stack: false
    .vgpr_count:     240
    .vgpr_spill_count: 0
    .wavefront_size: 64
  - .agpr_count:     0
    .args:
      - .offset:         0
        .size:           232
        .value_kind:     by_value
      - .offset:         232
        .size:           4
        .value_kind:     hidden_block_count_x
      - .offset:         236
        .size:           4
        .value_kind:     hidden_block_count_y
      - .offset:         240
        .size:           4
        .value_kind:     hidden_block_count_z
      - .offset:         244
        .size:           2
        .value_kind:     hidden_group_size_x
      - .offset:         246
        .size:           2
        .value_kind:     hidden_group_size_y
      - .offset:         248
        .size:           2
        .value_kind:     hidden_group_size_z
      - .offset:         250
        .size:           2
        .value_kind:     hidden_remainder_x
      - .offset:         252
        .size:           2
        .value_kind:     hidden_remainder_y
      - .offset:         254
        .size:           2
        .value_kind:     hidden_remainder_z
      - .offset:         272
        .size:           8
        .value_kind:     hidden_global_offset_x
      - .offset:         280
        .size:           8
        .value_kind:     hidden_global_offset_y
      - .offset:         288
        .size:           8
        .value_kind:     hidden_global_offset_z
      - .offset:         296
        .size:           2
        .value_kind:     hidden_grid_dims
    .group_segment_fixed_size: 0
    .kernarg_segment_align: 8
    .kernarg_segment_size: 488
    .language:       OpenCL C
    .language_version:
      - 2
      - 0
    .max_flat_workgroup_size: 512
    .name:           _Z10fwd_kernelILi4ELi5EEv4Args
    .private_segment_fixed_size: 0
    .sgpr_count:     58
    .sgpr_spill_count: 0
    .symbol:         _Z10fwd_kernelILi4ELi5EEv4Args.kd
    .uniform_work_group_size: 1
    .uses_dynamic_stack: false
    .vgpr_count:     192
    .vgpr_spill_count: 0
    .wavefront_size: 64
  - .agpr_count:     0
    .args:
      - .offset:         0
        .size:           232
        .value_kind:     by_value
      - .offset:         232
        .size:           4
        .value_kind:     hidden_block_count_x
      - .offset:         236
        .size:           4
        .value_kind:     hidden_block_count_y
      - .offset:         240
        .size:           4
        .value_kind:     hidden_block_count_z
      - .offset:         244
        .size:           2
        .value_kind:     hidden_group_size_x
      - .offset:         246
        .size:           2
        .value_kind:     hidden_group_size_y
      - .offset:         248
        .size:           2
        .value_kind:     hidden_group_size_z
      - .offset:         250
        .size:           2
        .value_kind:     hidden_remainder_x
      - .offset:         252
        .size:           2
        .value_kind:     hidden_remainder_y
      - .offset:         254
        .size:           2
        .value_kind:     hidden_remainder_z
      - .offset:         272
        .size:           8
        .value_kind:     hidden_global_offset_x
      - .offset:         280
        .size:           8
        .value_kind:     hidden_global_offset_y
      - .offset:         288
        .size:           8
        .value_kind:     hidden_global_offset_z
      - .offset:         296
        .size:           2
        .value_kind:     hidden_grid_dims
      - .offset:         352
        .size:           4
        .value_kind:     hidden_dynamic_lds_size
    .group_segment_fixed_size: 0
    .kernarg_segment_align: 8
    .kernarg_segment_size: 488
    .language:       OpenCL C
    .language_version:
      - 2
      - 0
    .max_flat_workgroup_size: 512
    .name:           _Z10fwd_kernelILi5ELi6EEv4Args
    .private_segment_fixed_size: 0
    .sgpr_count:     68
    .sgpr_spill_count: 0
    .symbol:         _Z10fwd_kernelILi5ELi6EEv4Args.kd
    .uniform_work_group_size: 1
    .uses_dynamic_stack: false
    .vgpr_count:     224
    .vgpr_spill_count: 0
    .wavefront_size: 64
  - .agpr_count:     0
    .args:
      - .offset:         0
        .size:           232
        .value_kind:     by_value
      - .offset:         232
        .size:           4
        .value_kind:     hidden_block_count_x
      - .offset:         236
        .size:           4
        .value_kind:     hidden_block_count_y
      - .offset:         240
        .size:           4
        .value_kind:     hidden_block_count_z
      - .offset:         244
        .size:           2
        .value_kind:     hidden_group_size_x
      - .offset:         246
        .size:           2
        .value_kind:     hidden_group_size_y
      - .offset:         248
        .size:           2
        .value_kind:     hidden_group_size_z
      - .offset:         250
        .size:           2
        .value_kind:     hidden_remainder_x
      - .offset:         252
        .size:           2
        .value_kind:     hidden_remainder_y
      - .offset:         254
        .size:           2
        .value_kind:     hidden_remainder_z
      - .offset:         272
        .size:           8
        .value_kind:     hidden_global_offset_x
      - .offset:         280
        .size:           8
        .value_kind:     hidden_global_offset_y
      - .offset:         288
        .size:           8
        .value_kind:     hidden_global_offset_z
      - .offset:         296
        .size:           2
        .value_kind:     hidden_grid_dims
      - .offset:         352
        .size:           4
        .value_kind:     hidden_dynamic_lds_size
    .group_segment_fixed_size: 0
    .kernarg_segment_align: 8
    .kernarg_segment_size: 488
    .language:       OpenCL C
    .language_version:
      - 2
      - 0
    .max_flat_workgroup_size: 512
    .name:           _Z10fwd_kernelILi6ELi7EEv4Args
    .private_segment_fixed_size: 0
    .sgpr_count:     67
    .sgpr_spill_count: 0
    .symbol:         _Z10fwd_kernelILi6ELi7EEv4Args.kd
    .uniform_work_group_size: 1
    .uses_dynamic_stack: false
    .vgpr_count:     240
    .vgpr_spill_count: 0
    .wavefront_size: 64
  - .agpr_count:     0
    .args:
      - .offset:         0
        .size:           232
        .value_kind:     by_value
      - .offset:         232
        .size:           4
        .value_kind:     hidden_block_count_x
      - .offset:         236
        .size:           4
        .value_kind:     hidden_block_count_y
      - .offset:         240
        .size:           4
        .value_kind:     hidden_block_count_z
      - .offset:         244
        .size:           2
        .value_kind:     hidden_group_size_x
      - .offset:         246
        .size:           2
        .value_kind:     hidden_group_size_y
      - .offset:         248
        .size:           2
        .value_kind:     hidden_group_size_z
      - .offset:         250
        .size:           2
        .value_kind:     hidden_remainder_x
      - .offset:         252
        .size:           2
        .value_kind:     hidden_remainder_y
      - .offset:         254
        .size:           2
        .value_kind:     hidden_remainder_z
      - .offset:         272
        .size:           8
        .value_kind:     hidden_global_offset_x
      - .offset:         280
        .size:           8
        .value_kind:     hidden_global_offset_y
      - .offset:         288
        .size:           8
        .value_kind:     hidden_global_offset_z
      - .offset:         296
        .size:           2
        .value_kind:     hidden_grid_dims
    .group_segment_fixed_size: 0
    .kernarg_segment_align: 8
    .kernarg_segment_size: 488
    .language:       OpenCL C
    .language_version:
      - 2
      - 0
    .max_flat_workgroup_size: 512
    .name:           _Z10fwd_kernelILi7ELi8EEv4Args
    .private_segment_fixed_size: 0
    .sgpr_count:     42
    .sgpr_spill_count: 0
    .symbol:         _Z10fwd_kernelILi7ELi8EEv4Args.kd
    .uniform_work_group_size: 1
    .uses_dynamic_stack: false
    .vgpr_count:     204
    .vgpr_spill_count: 0
    .wavefront_size: 64
  - .agpr_count:     0
    .args:
      - .offset:         0
        .size:           232
        .value_kind:     by_value
      - .offset:         232
        .size:           4
        .value_kind:     hidden_block_count_x
      - .offset:         236
        .size:           4
        .value_kind:     hidden_block_count_y
      - .offset:         240
        .size:           4
        .value_kind:     hidden_block_count_z
      - .offset:         244
        .size:           2
        .value_kind:     hidden_group_size_x
      - .offset:         246
        .size:           2
        .value_kind:     hidden_group_size_y
      - .offset:         248
        .size:           2
        .value_kind:     hidden_group_size_z
      - .offset:         250
        .size:           2
        .value_kind:     hidden_remainder_x
      - .offset:         252
        .size:           2
        .value_kind:     hidden_remainder_y
      - .offset:         254
        .size:           2
        .value_kind:     hidden_remainder_z
      - .offset:         272
        .size:           8
        .value_kind:     hidden_global_offset_x
      - .offset:         280
        .size:           8
        .value_kind:     hidden_global_offset_y
      - .offset:         288
        .size:           8
        .value_kind:     hidden_global_offset_z
      - .offset:         296
        .size:           2
        .value_kind:     hidden_grid_dims
      - .offset:         352
        .size:           4
        .value_kind:     hidden_dynamic_lds_size
    .group_segment_fixed_size: 0
    .kernarg_segment_align: 8
    .kernarg_segment_size: 488
    .language:       OpenCL C
    .language_version:
      - 2
      - 0
    .max_flat_workgroup_size: 512
    .name:           _Z10fwd_kernelILi8ELi9EEv4Args
    .private_segment_fixed_size: 0
    .sgpr_count:     75
    .sgpr_spill_count: 0
    .symbol:         _Z10fwd_kernelILi8ELi9EEv4Args.kd
    .uniform_work_group_size: 1
    .uses_dynamic_stack: false
    .vgpr_count:     226
    .vgpr_spill_count: 0
    .wavefront_size: 64
  - .agpr_count:     0
    .args:
      - .offset:         0
        .size:           232
        .value_kind:     by_value
      - .offset:         232
        .size:           4
        .value_kind:     hidden_block_count_x
      - .offset:         236
        .size:           4
        .value_kind:     hidden_block_count_y
      - .offset:         240
        .size:           4
        .value_kind:     hidden_block_count_z
      - .offset:         244
        .size:           2
        .value_kind:     hidden_group_size_x
      - .offset:         246
        .size:           2
        .value_kind:     hidden_group_size_y
      - .offset:         248
        .size:           2
        .value_kind:     hidden_group_size_z
      - .offset:         250
        .size:           2
        .value_kind:     hidden_remainder_x
      - .offset:         252
        .size:           2
        .value_kind:     hidden_remainder_y
      - .offset:         254
        .size:           2
        .value_kind:     hidden_remainder_z
      - .offset:         272
        .size:           8
        .value_kind:     hidden_global_offset_x
      - .offset:         280
        .size:           8
        .value_kind:     hidden_global_offset_y
      - .offset:         288
        .size:           8
        .value_kind:     hidden_global_offset_z
      - .offset:         296
        .size:           2
        .value_kind:     hidden_grid_dims
      - .offset:         352
        .size:           4
        .value_kind:     hidden_dynamic_lds_size
    .group_segment_fixed_size: 0
    .kernarg_segment_align: 8
    .kernarg_segment_size: 488
    .language:       OpenCL C
    .language_version:
      - 2
      - 0
    .max_flat_workgroup_size: 512
    .name:           _Z10fwd_kernelILi9ELi10EEv4Args
    .private_segment_fixed_size: 0
    .sgpr_count:     80
    .sgpr_spill_count: 0
    .symbol:         _Z10fwd_kernelILi9ELi10EEv4Args.kd
    .uniform_work_group_size: 1
    .uses_dynamic_stack: false
    .vgpr_count:     174
    .vgpr_spill_count: 0
    .wavefront_size: 64
  - .agpr_count:     0
    .args:
      - .offset:         0
        .size:           232
        .value_kind:     by_value
      - .offset:         232
        .size:           4
        .value_kind:     hidden_block_count_x
      - .offset:         236
        .size:           4
        .value_kind:     hidden_block_count_y
      - .offset:         240
        .size:           4
        .value_kind:     hidden_block_count_z
      - .offset:         244
        .size:           2
        .value_kind:     hidden_group_size_x
      - .offset:         246
        .size:           2
        .value_kind:     hidden_group_size_y
      - .offset:         248
        .size:           2
        .value_kind:     hidden_group_size_z
      - .offset:         250
        .size:           2
        .value_kind:     hidden_remainder_x
      - .offset:         252
        .size:           2
        .value_kind:     hidden_remainder_y
      - .offset:         254
        .size:           2
        .value_kind:     hidden_remainder_z
      - .offset:         272
        .size:           8
        .value_kind:     hidden_global_offset_x
      - .offset:         280
        .size:           8
        .value_kind:     hidden_global_offset_y
      - .offset:         288
        .size:           8
        .value_kind:     hidden_global_offset_z
      - .offset:         296
        .size:           2
        .value_kind:     hidden_grid_dims
      - .offset:         352
        .size:           4
        .value_kind:     hidden_dynamic_lds_size
    .group_segment_fixed_size: 0
    .kernarg_segment_align: 8
    .kernarg_segment_size: 488
    .language:       OpenCL C
    .language_version:
      - 2
      - 0
    .max_flat_workgroup_size: 512
    .name:           _Z10fwd_kernelILi10ELi11EEv4Args
    .private_segment_fixed_size: 0
    .sgpr_count:     67
    .sgpr_spill_count: 0
    .symbol:         _Z10fwd_kernelILi10ELi11EEv4Args.kd
    .uniform_work_group_size: 1
    .uses_dynamic_stack: false
    .vgpr_count:     240
    .vgpr_spill_count: 0
    .wavefront_size: 64
  - .agpr_count:     0
    .args:
      - .offset:         0
        .size:           232
        .value_kind:     by_value
      - .offset:         232
        .size:           4
        .value_kind:     hidden_block_count_x
      - .offset:         236
        .size:           4
        .value_kind:     hidden_block_count_y
      - .offset:         240
        .size:           4
        .value_kind:     hidden_block_count_z
      - .offset:         244
        .size:           2
        .value_kind:     hidden_group_size_x
      - .offset:         246
        .size:           2
        .value_kind:     hidden_group_size_y
      - .offset:         248
        .size:           2
        .value_kind:     hidden_group_size_z
      - .offset:         250
        .size:           2
        .value_kind:     hidden_remainder_x
      - .offset:         252
        .size:           2
        .value_kind:     hidden_remainder_y
      - .offset:         254
        .size:           2
        .value_kind:     hidden_remainder_z
      - .offset:         272
        .size:           8
        .value_kind:     hidden_global_offset_x
      - .offset:         280
        .size:           8
        .value_kind:     hidden_global_offset_y
      - .offset:         288
        .size:           8
        .value_kind:     hidden_global_offset_z
      - .offset:         296
        .size:           2
        .value_kind:     hidden_grid_dims
    .group_segment_fixed_size: 0
    .kernarg_segment_align: 8
    .kernarg_segment_size: 488
    .language:       OpenCL C
    .language_version:
      - 2
      - 0
    .max_flat_workgroup_size: 512
    .name:           _Z10fwd_kernelILi11ELi12EEv4Args
    .private_segment_fixed_size: 0
    .sgpr_count:     42
    .sgpr_spill_count: 0
    .symbol:         _Z10fwd_kernelILi11ELi12EEv4Args.kd
    .uniform_work_group_size: 1
    .uses_dynamic_stack: false
    .vgpr_count:     192
    .vgpr_spill_count: 0
    .wavefront_size: 64
  - .agpr_count:     0
    .args:
      - .offset:         0
        .size:           232
        .value_kind:     by_value
      - .offset:         232
        .size:           4
        .value_kind:     hidden_block_count_x
      - .offset:         236
        .size:           4
        .value_kind:     hidden_block_count_y
      - .offset:         240
        .size:           4
        .value_kind:     hidden_block_count_z
      - .offset:         244
        .size:           2
        .value_kind:     hidden_group_size_x
      - .offset:         246
        .size:           2
        .value_kind:     hidden_group_size_y
      - .offset:         248
        .size:           2
        .value_kind:     hidden_group_size_z
      - .offset:         250
        .size:           2
        .value_kind:     hidden_remainder_x
      - .offset:         252
        .size:           2
        .value_kind:     hidden_remainder_y
      - .offset:         254
        .size:           2
        .value_kind:     hidden_remainder_z
      - .offset:         272
        .size:           8
        .value_kind:     hidden_global_offset_x
      - .offset:         280
        .size:           8
        .value_kind:     hidden_global_offset_y
      - .offset:         288
        .size:           8
        .value_kind:     hidden_global_offset_z
      - .offset:         296
        .size:           2
        .value_kind:     hidden_grid_dims
      - .offset:         352
        .size:           4
        .value_kind:     hidden_dynamic_lds_size
    .group_segment_fixed_size: 0
    .kernarg_segment_align: 8
    .kernarg_segment_size: 488
    .language:       OpenCL C
    .language_version:
      - 2
      - 0
    .max_flat_workgroup_size: 512
    .name:           _Z10fwd_kernelILi12ELi13EEv4Args
    .private_segment_fixed_size: 0
    .sgpr_count:     68
    .sgpr_spill_count: 0
    .symbol:         _Z10fwd_kernelILi12ELi13EEv4Args.kd
    .uniform_work_group_size: 1
    .uses_dynamic_stack: false
    .vgpr_count:     224
    .vgpr_spill_count: 0
    .wavefront_size: 64
  - .agpr_count:     0
    .args:
      - .offset:         0
        .size:           232
        .value_kind:     by_value
      - .offset:         232
        .size:           4
        .value_kind:     hidden_block_count_x
      - .offset:         236
        .size:           4
        .value_kind:     hidden_block_count_y
      - .offset:         240
        .size:           4
        .value_kind:     hidden_block_count_z
      - .offset:         244
        .size:           2
        .value_kind:     hidden_group_size_x
      - .offset:         246
        .size:           2
        .value_kind:     hidden_group_size_y
      - .offset:         248
        .size:           2
        .value_kind:     hidden_group_size_z
      - .offset:         250
        .size:           2
        .value_kind:     hidden_remainder_x
      - .offset:         252
        .size:           2
        .value_kind:     hidden_remainder_y
      - .offset:         254
        .size:           2
        .value_kind:     hidden_remainder_z
      - .offset:         272
        .size:           8
        .value_kind:     hidden_global_offset_x
      - .offset:         280
        .size:           8
        .value_kind:     hidden_global_offset_y
      - .offset:         288
        .size:           8
        .value_kind:     hidden_global_offset_z
      - .offset:         296
        .size:           2
        .value_kind:     hidden_grid_dims
      - .offset:         352
        .size:           4
        .value_kind:     hidden_dynamic_lds_size
    .group_segment_fixed_size: 0
    .kernarg_segment_align: 8
    .kernarg_segment_size: 488
    .language:       OpenCL C
    .language_version:
      - 2
      - 0
    .max_flat_workgroup_size: 512
    .name:           _Z10fwd_kernelILi13ELi14EEv4Args
    .private_segment_fixed_size: 0
    .sgpr_count:     67
    .sgpr_spill_count: 0
    .symbol:         _Z10fwd_kernelILi13ELi14EEv4Args.kd
    .uniform_work_group_size: 1
    .uses_dynamic_stack: false
    .vgpr_count:     240
    .vgpr_spill_count: 0
    .wavefront_size: 64
  - .agpr_count:     0
    .args:
      - .offset:         0
        .size:           232
        .value_kind:     by_value
      - .offset:         232
        .size:           4
        .value_kind:     hidden_block_count_x
      - .offset:         236
        .size:           4
        .value_kind:     hidden_block_count_y
      - .offset:         240
        .size:           4
        .value_kind:     hidden_block_count_z
      - .offset:         244
        .size:           2
        .value_kind:     hidden_group_size_x
      - .offset:         246
        .size:           2
        .value_kind:     hidden_group_size_y
      - .offset:         248
        .size:           2
        .value_kind:     hidden_group_size_z
      - .offset:         250
        .size:           2
        .value_kind:     hidden_remainder_x
      - .offset:         252
        .size:           2
        .value_kind:     hidden_remainder_y
      - .offset:         254
        .size:           2
        .value_kind:     hidden_remainder_z
      - .offset:         272
        .size:           8
        .value_kind:     hidden_global_offset_x
      - .offset:         280
        .size:           8
        .value_kind:     hidden_global_offset_y
      - .offset:         288
        .size:           8
        .value_kind:     hidden_global_offset_z
      - .offset:         296
        .size:           2
        .value_kind:     hidden_grid_dims
    .group_segment_fixed_size: 0
    .kernarg_segment_align: 8
    .kernarg_segment_size: 488
    .language:       OpenCL C
    .language_version:
      - 2
      - 0
    .max_flat_workgroup_size: 512
    .name:           _Z10fwd_kernelILi14ELi15EEv4Args
    .private_segment_fixed_size: 0
    .sgpr_count:     42
    .sgpr_spill_count: 0
    .symbol:         _Z10fwd_kernelILi14ELi15EEv4Args.kd
    .uniform_work_group_size: 1
    .uses_dynamic_stack: false
    .vgpr_count:     186
    .vgpr_spill_count: 0
    .wavefront_size: 64
